# GEMM K-loops: removed the post-barrier lgkmcnt(0) already satisfied before the barrier and the back-to-back s_setprio 0/1 pairs between MFMA blocks
# baseline (speedup 1.0000x reference)
.LBB0_72:
	s_add_u32 s14, s12, 0xfffc0080
	s_addc_u32 s15, s13, -1
	s_add_i32 s24, 0, 0x10000
	s_cmp_eq_u32 s96, 12
	s_cselect_b32 s45, s39, s15
	s_cselect_b32 s44, s54, s14
	v_add_u32_e32 v2, s24, v185
	s_cselect_b32 s15, s29, s61
	s_cselect_b32 s14, s55, s60
	s_add_i32 s25, 0, 0x14000
	ds_read_b128 v[142:145], v2
	ds_read_b128 v[146:149], v2 offset:1024
	ds_read_b128 v[150:153], v2 offset:2048
	ds_read_b128 v[172:175], v2 offset:3072
	v_add_u32_e32 v2, s25, v185
	ds_read_b128 v[176:179], v2
	ds_read_b128 v[180:183], v2 offset:1024
	ds_read_b128 v[188:191], v2 offset:2048
	ds_read_b128 v[200:203], v2 offset:3072
	v_lshl_add_u64 v[154:155], s[12:13], 0, v[140:141]
	s_add_i32 m0, s21, 0xc000
	ds_read_b128 v[204:207], v187
	ds_read_b128 v[208:211], v187 offset:1024
	ds_read_b128 v[212:215], v187 offset:2048
	ds_read_b128 v[216:219], v187 offset:3072
	ds_read_b128 v[220:223], v187 offset:4096
	ds_read_b128 v[224:227], v187 offset:5120
	ds_read_b128 v[228:231], v187 offset:6144
	ds_read_b128 v[232:235], v187 offset:7168
	global_load_lds_dwordx4 v[154:155], off
	v_lshl_add_u64 v[154:155], s[12:13], 0, v[138:139]
	s_add_i32 m0, s21, 0xe000
	s_nop 0
	global_load_lds_dwordx4 v[154:155], off
	s_waitcnt vmcnt(8)
	s_waitcnt lgkmcnt(0)
	s_barrier
	s_setprio 1
	v_mfma_f32_16x16x32_bf16 v[128:131], v[142:145], v[204:207], v[128:131]
	v_mfma_f32_16x16x32_bf16 v[124:127], v[150:153], v[204:207], v[124:127]
	v_mfma_f32_16x16x32_bf16 v[112:115], v[142:145], v[212:215], v[112:115]
	v_mfma_f32_16x16x32_bf16 v[108:111], v[150:153], v[212:215], v[108:111]
	v_mfma_f32_16x16x32_bf16 v[96:99], v[142:145], v[220:223], v[96:99]
	v_mfma_f32_16x16x32_bf16 v[92:95], v[150:153], v[220:223], v[92:95]
	v_mfma_f32_16x16x32_bf16 v[80:83], v[142:145], v[228:231], v[80:83]
	v_mfma_f32_16x16x32_bf16 v[76:79], v[150:153], v[228:231], v[76:79]
	v_mfma_f32_16x16x32_bf16 v[128:131], v[146:149], v[208:211], v[128:131]
	v_mfma_f32_16x16x32_bf16 v[124:127], v[172:175], v[208:211], v[124:127]
	v_mfma_f32_16x16x32_bf16 v[112:115], v[146:149], v[216:219], v[112:115]
	v_mfma_f32_16x16x32_bf16 v[108:111], v[172:175], v[216:219], v[108:111]
	v_mfma_f32_16x16x32_bf16 v[96:99], v[146:149], v[224:227], v[96:99]
	v_mfma_f32_16x16x32_bf16 v[92:95], v[172:175], v[224:227], v[92:95]
	v_mfma_f32_16x16x32_bf16 v[80:83], v[146:149], v[232:235], v[80:83]
	v_mfma_f32_16x16x32_bf16 v[76:79], v[172:175], v[232:235], v[76:79]
	v_mfma_f32_16x16x32_bf16 v[120:123], v[176:179], v[204:207], v[120:123]
	v_mfma_f32_16x16x32_bf16 v[116:119], v[188:191], v[204:207], v[116:119]
	v_mfma_f32_16x16x32_bf16 v[104:107], v[176:179], v[212:215], v[104:107]
	v_mfma_f32_16x16x32_bf16 v[100:103], v[188:191], v[212:215], v[100:103]
	v_mfma_f32_16x16x32_bf16 v[88:91], v[176:179], v[220:223], v[88:91]
	v_mfma_f32_16x16x32_bf16 v[84:87], v[188:191], v[220:223], v[84:87]
	v_mfma_f32_16x16x32_bf16 v[72:75], v[176:179], v[228:231], v[72:75]
	v_mfma_f32_16x16x32_bf16 v[68:71], v[188:191], v[228:231], v[68:71]
	v_mfma_f32_16x16x32_bf16 v[120:123], v[180:183], v[208:211], v[120:123]
	v_mfma_f32_16x16x32_bf16 v[116:119], v[200:203], v[208:211], v[116:119]
	v_mfma_f32_16x16x32_bf16 v[104:107], v[180:183], v[216:219], v[104:107]
	v_mfma_f32_16x16x32_bf16 v[100:103], v[200:203], v[216:219], v[100:103]
	v_mfma_f32_16x16x32_bf16 v[88:91], v[180:183], v[224:227], v[88:91]
	v_mfma_f32_16x16x32_bf16 v[84:87], v[200:203], v[224:227], v[84:87]
	v_mfma_f32_16x16x32_bf16 v[72:75], v[180:183], v[232:235], v[72:75]
	v_mfma_f32_16x16x32_bf16 v[68:71], v[200:203], v[232:235], v[68:71]
	s_setprio 0
	s_barrier
	s_add_i32 s24, s24, s20
	v_lshl_add_u64 v[154:155], s[14:15], 0, v[134:135]
	s_mov_b32 m0, s24
	ds_read_b128 v[204:207], v187 offset:16384
	ds_read_b128 v[208:211], v187 offset:17408
	ds_read_b128 v[212:215], v187 offset:18432
	ds_read_b128 v[216:219], v187 offset:19456
	ds_read_b128 v[220:223], v187 offset:20480
	ds_read_b128 v[224:227], v187 offset:21504
	ds_read_b128 v[228:231], v187 offset:22528
	ds_read_b128 v[232:235], v187 offset:23552
	global_load_lds_dwordx4 v[154:155], off
	s_add_i32 m0, s24, 0x2000
	s_add_u32 vcc_lo, s14, 0x40000
	v_lshl_add_u64 v[192:193], s[14:15], 0, v[0:1]
	s_addc_u32 vcc_hi, s15, 0
	s_add_i32 s24, s25, s20
	global_load_lds_dwordx4 v[192:193], off
	v_lshl_add_u64 v[236:237], vcc, 0, v[134:135]
	s_mov_b32 m0, s24
	v_lshl_add_u64 v[238:239], s[44:45], 0, v[132:133]
	global_load_lds_dwordx4 v[236:237], off
	v_lshl_add_u64 v[236:237], vcc, 0, v[0:1]
	s_add_i32 m0, s24, 0x2000
	s_nop 0
	global_load_lds_dwordx4 v[236:237], off
	v_lshl_add_u64 v[236:237], s[44:45], 0, v[136:137]
	s_mov_b32 m0, s21
	s_nop 0
	global_load_lds_dwordx4 v[236:237], off
	s_mov_b32 m0, s22
	s_nop 0
	global_load_lds_dwordx4 v[238:239], off
	s_waitcnt vmcnt(8)
	s_waitcnt lgkmcnt(0)
	s_barrier
	s_setprio 1
	v_mfma_f32_16x16x32_bf16 v[64:67], v[142:145], v[204:207], v[64:67]
	v_mfma_f32_16x16x32_bf16 v[60:63], v[150:153], v[204:207], v[60:63]
	v_mfma_f32_16x16x32_bf16 v[48:51], v[142:145], v[212:215], v[48:51]
	v_mfma_f32_16x16x32_bf16 v[44:47], v[150:153], v[212:215], v[44:47]
	v_mfma_f32_16x16x32_bf16 v[32:35], v[142:145], v[220:223], v[32:35]
	v_mfma_f32_16x16x32_bf16 v[28:31], v[150:153], v[220:223], v[28:31]
	v_mfma_f32_16x16x32_bf16 v[16:19], v[142:145], v[228:231], v[16:19]
	v_mfma_f32_16x16x32_bf16 v[12:15], v[150:153], v[228:231], v[12:15]
	v_mfma_f32_16x16x32_bf16 v[64:67], v[146:149], v[208:211], v[64:67]
	v_mfma_f32_16x16x32_bf16 v[60:63], v[172:175], v[208:211], v[60:63]
	v_mfma_f32_16x16x32_bf16 v[48:51], v[146:149], v[216:219], v[48:51]
	v_mfma_f32_16x16x32_bf16 v[44:47], v[172:175], v[216:219], v[44:47]
	v_mfma_f32_16x16x32_bf16 v[32:35], v[146:149], v[224:227], v[32:35]
	v_mfma_f32_16x16x32_bf16 v[28:31], v[172:175], v[224:227], v[28:31]
	v_mfma_f32_16x16x32_bf16 v[16:19], v[146:149], v[232:235], v[16:19]
	v_mfma_f32_16x16x32_bf16 v[12:15], v[172:175], v[232:235], v[12:15]
	v_mfma_f32_16x16x32_bf16 v[56:59], v[176:179], v[204:207], v[56:59]
	v_mfma_f32_16x16x32_bf16 v[52:55], v[188:191], v[204:207], v[52:55]
	v_mfma_f32_16x16x32_bf16 v[40:43], v[176:179], v[212:215], v[40:43]
	v_mfma_f32_16x16x32_bf16 v[36:39], v[188:191], v[212:215], v[36:39]
	v_mfma_f32_16x16x32_bf16 v[24:27], v[176:179], v[220:223], v[24:27]
	v_mfma_f32_16x16x32_bf16 v[20:23], v[188:191], v[220:223], v[20:23]
	v_mfma_f32_16x16x32_bf16 v[8:11], v[176:179], v[228:231], v[8:11]
	v_mfma_f32_16x16x32_bf16 v[4:7], v[188:191], v[228:231], v[4:7]
	v_mfma_f32_16x16x32_bf16 v[56:59], v[180:183], v[208:211], v[56:59]
	v_mfma_f32_16x16x32_bf16 v[52:55], v[200:203], v[208:211], v[52:55]
	v_mfma_f32_16x16x32_bf16 v[40:43], v[180:183], v[216:219], v[40:43]
	v_mfma_f32_16x16x32_bf16 v[36:39], v[200:203], v[216:219], v[36:39]
	v_mfma_f32_16x16x32_bf16 v[24:27], v[180:183], v[224:227], v[24:27]
	v_mfma_f32_16x16x32_bf16 v[20:23], v[200:203], v[224:227], v[20:23]
	v_mfma_f32_16x16x32_bf16 v[8:11], v[180:183], v[232:235], v[8:11]
	v_mfma_f32_16x16x32_bf16 v[4:7], v[200:203], v[232:235], v[4:7]
	s_setprio 0
	s_barrier
	s_add_i32 s24, 0, 0x18000
	v_add_u32_e32 v2, s24, v185
	s_add_i32 s25, 0, 0x1c000
	ds_read_b128 v[142:145], v2
	ds_read_b128 v[146:149], v2 offset:1024
	ds_read_b128 v[150:153], v2 offset:2048
	ds_read_b128 v[172:175], v2 offset:3072
	v_add_u32_e32 v2, s25, v185
	ds_read_b128 v[176:179], v2
	ds_read_b128 v[180:183], v2 offset:1024
	ds_read_b128 v[188:191], v2 offset:2048
	ds_read_b128 v[200:203], v2 offset:3072
	s_add_u32 s44, s44, 0x40000
	s_addc_u32 s45, s45, 0
	s_mov_b32 m0, s23
	v_lshl_add_u64 v[240:241], s[44:45], 0, v[136:137]
	ds_read_b128 v[204:207], v187 offset:32768
	ds_read_b128 v[208:211], v187 offset:33792
	ds_read_b128 v[212:215], v187 offset:34816
	ds_read_b128 v[216:219], v187 offset:35840
	ds_read_b128 v[220:223], v187 offset:36864
	ds_read_b128 v[224:227], v187 offset:37888
	ds_read_b128 v[228:231], v187 offset:38912
	ds_read_b128 v[232:235], v187 offset:39936
	global_load_lds_dwordx4 v[240:241], off
	v_lshl_add_u64 v[240:241], s[44:45], 0, v[132:133]
	s_mov_b32 m0, s36
	s_nop 0
	global_load_lds_dwordx4 v[240:241], off
	s_waitcnt vmcnt(8)
	s_waitcnt lgkmcnt(0)
	s_barrier
	s_setprio 1
	v_mfma_f32_16x16x32_bf16 v[128:131], v[142:145], v[204:207], v[128:131]
	v_mfma_f32_16x16x32_bf16 v[124:127], v[150:153], v[204:207], v[124:127]
	v_mfma_f32_16x16x32_bf16 v[112:115], v[142:145], v[212:215], v[112:115]
	v_mfma_f32_16x16x32_bf16 v[108:111], v[150:153], v[212:215], v[108:111]
	v_mfma_f32_16x16x32_bf16 v[96:99], v[142:145], v[220:223], v[96:99]
	v_mfma_f32_16x16x32_bf16 v[92:95], v[150:153], v[220:223], v[92:95]
	v_mfma_f32_16x16x32_bf16 v[80:83], v[142:145], v[228:231], v[80:83]
	v_mfma_f32_16x16x32_bf16 v[76:79], v[150:153], v[228:231], v[76:79]
	v_mfma_f32_16x16x32_bf16 v[128:131], v[146:149], v[208:211], v[128:131]
	v_mfma_f32_16x16x32_bf16 v[124:127], v[172:175], v[208:211], v[124:127]
	v_mfma_f32_16x16x32_bf16 v[112:115], v[146:149], v[216:219], v[112:115]
	v_mfma_f32_16x16x32_bf16 v[108:111], v[172:175], v[216:219], v[108:111]
	v_mfma_f32_16x16x32_bf16 v[96:99], v[146:149], v[224:227], v[96:99]
	v_mfma_f32_16x16x32_bf16 v[92:95], v[172:175], v[224:227], v[92:95]
	v_mfma_f32_16x16x32_bf16 v[80:83], v[146:149], v[232:235], v[80:83]
	v_mfma_f32_16x16x32_bf16 v[76:79], v[172:175], v[232:235], v[76:79]
	v_mfma_f32_16x16x32_bf16 v[120:123], v[176:179], v[204:207], v[120:123]
	v_mfma_f32_16x16x32_bf16 v[116:119], v[188:191], v[204:207], v[116:119]
	v_mfma_f32_16x16x32_bf16 v[104:107], v[176:179], v[212:215], v[104:107]
	v_mfma_f32_16x16x32_bf16 v[100:103], v[188:191], v[212:215], v[100:103]
	v_mfma_f32_16x16x32_bf16 v[88:91], v[176:179], v[220:223], v[88:91]
	v_mfma_f32_16x16x32_bf16 v[84:87], v[188:191], v[220:223], v[84:87]
	v_mfma_f32_16x16x32_bf16 v[72:75], v[176:179], v[228:231], v[72:75]
	v_mfma_f32_16x16x32_bf16 v[68:71], v[188:191], v[228:231], v[68:71]
	v_mfma_f32_16x16x32_bf16 v[120:123], v[180:183], v[208:211], v[120:123]
	v_mfma_f32_16x16x32_bf16 v[116:119], v[200:203], v[208:211], v[116:119]
	v_mfma_f32_16x16x32_bf16 v[104:107], v[180:183], v[216:219], v[104:107]
	v_mfma_f32_16x16x32_bf16 v[100:103], v[200:203], v[216:219], v[100:103]
	v_mfma_f32_16x16x32_bf16 v[88:91], v[180:183], v[224:227], v[88:91]
	v_mfma_f32_16x16x32_bf16 v[84:87], v[200:203], v[224:227], v[84:87]
	v_mfma_f32_16x16x32_bf16 v[72:75], v[180:183], v[232:235], v[72:75]
	v_mfma_f32_16x16x32_bf16 v[68:71], v[200:203], v[232:235], v[68:71]
	s_setprio 0
	s_barrier
	s_add_i32 s24, s24, s20
	v_lshl_add_u64 v[154:155], v[154:155], 0, s[26:27]
	s_mov_b32 m0, s24
	ds_read_b128 v[204:207], v187 offset:49152
	ds_read_b128 v[208:211], v187 offset:50176
	ds_read_b128 v[212:215], v187 offset:51200
	ds_read_b128 v[216:219], v187 offset:52224
	ds_read_b128 v[220:223], v187 offset:53248
	ds_read_b128 v[224:227], v187 offset:54272
	ds_read_b128 v[228:231], v187 offset:55296
	ds_read_b128 v[232:235], v187 offset:56320
	global_load_lds_dwordx4 v[154:155], off
	s_add_i32 m0, s24, 0x2000
	s_add_u32 s14, s14, 0x40080
	v_lshl_add_u64 v[154:155], v[192:193], 0, s[26:27]
	s_addc_u32 s15, s15, 0
	s_add_i32 s24, s25, s20
	global_load_lds_dwordx4 v[154:155], off
	v_lshl_add_u64 v[154:155], s[14:15], 0, v[134:135]
	s_mov_b32 m0, s24
	s_nop 0
	global_load_lds_dwordx4 v[154:155], off
	v_lshl_add_u64 v[154:155], s[14:15], 0, v[0:1]
	s_add_i32 m0, s24, 0x2000
	s_nop 0
	global_load_lds_dwordx4 v[154:155], off
	v_lshl_add_u64 v[154:155], v[236:237], 0, s[26:27]
	s_mov_b32 m0, s77
	s_nop 0
	global_load_lds_dwordx4 v[154:155], off
	v_lshl_add_u64 v[154:155], v[238:239], 0, s[26:27]
	s_mov_b32 m0, s87
	s_nop 0
	global_load_lds_dwordx4 v[154:155], off
	s_waitcnt vmcnt(8)
	s_waitcnt lgkmcnt(0)
	s_barrier
	s_setprio 1
	v_mfma_f32_16x16x32_bf16 v[64:67], v[142:145], v[204:207], v[64:67]
	v_mfma_f32_16x16x32_bf16 v[60:63], v[150:153], v[204:207], v[60:63]
	v_mfma_f32_16x16x32_bf16 v[48:51], v[142:145], v[212:215], v[48:51]
	v_mfma_f32_16x16x32_bf16 v[44:47], v[150:153], v[212:215], v[44:47]
	v_mfma_f32_16x16x32_bf16 v[32:35], v[142:145], v[220:223], v[32:35]
	v_mfma_f32_16x16x32_bf16 v[28:31], v[150:153], v[220:223], v[28:31]
	v_mfma_f32_16x16x32_bf16 v[16:19], v[142:145], v[228:231], v[16:19]
	v_mfma_f32_16x16x32_bf16 v[12:15], v[150:153], v[228:231], v[12:15]
	v_mfma_f32_16x16x32_bf16 v[64:67], v[146:149], v[208:211], v[64:67]
	v_mfma_f32_16x16x32_bf16 v[60:63], v[172:175], v[208:211], v[60:63]
	v_mfma_f32_16x16x32_bf16 v[48:51], v[146:149], v[216:219], v[48:51]
	v_mfma_f32_16x16x32_bf16 v[44:47], v[172:175], v[216:219], v[44:47]
	v_mfma_f32_16x16x32_bf16 v[32:35], v[146:149], v[224:227], v[32:35]
	v_mfma_f32_16x16x32_bf16 v[28:31], v[172:175], v[224:227], v[28:31]
	v_mfma_f32_16x16x32_bf16 v[16:19], v[146:149], v[232:235], v[16:19]
	v_mfma_f32_16x16x32_bf16 v[12:15], v[172:175], v[232:235], v[12:15]
	v_mfma_f32_16x16x32_bf16 v[56:59], v[176:179], v[204:207], v[56:59]
	v_mfma_f32_16x16x32_bf16 v[52:55], v[188:191], v[204:207], v[52:55]
	v_mfma_f32_16x16x32_bf16 v[40:43], v[176:179], v[212:215], v[40:43]
	v_mfma_f32_16x16x32_bf16 v[36:39], v[188:191], v[212:215], v[36:39]
	v_mfma_f32_16x16x32_bf16 v[24:27], v[176:179], v[220:223], v[24:27]
	v_mfma_f32_16x16x32_bf16 v[20:23], v[188:191], v[220:223], v[20:23]
	v_mfma_f32_16x16x32_bf16 v[8:11], v[176:179], v[228:231], v[8:11]
	v_mfma_f32_16x16x32_bf16 v[4:7], v[188:191], v[228:231], v[4:7]
	v_mfma_f32_16x16x32_bf16 v[56:59], v[180:183], v[208:211], v[56:59]
	v_mfma_f32_16x16x32_bf16 v[52:55], v[200:203], v[208:211], v[52:55]
	v_mfma_f32_16x16x32_bf16 v[40:43], v[180:183], v[216:219], v[40:43]
	v_mfma_f32_16x16x32_bf16 v[36:39], v[200:203], v[216:219], v[36:39]
	v_mfma_f32_16x16x32_bf16 v[24:27], v[180:183], v[224:227], v[24:27]
	v_mfma_f32_16x16x32_bf16 v[20:23], v[200:203], v[224:227], v[20:23]
	v_mfma_f32_16x16x32_bf16 v[8:11], v[180:183], v[232:235], v[8:11]
	v_mfma_f32_16x16x32_bf16 v[4:7], v[200:203], v[232:235], v[4:7]
	s_setprio 0
	s_barrier
	s_add_i32 s96, s96, 2
	s_add_u32 s60, s60, 0x100
	s_addc_u32 s61, s61, 0
	s_add_u32 s12, s12, 0x100
	s_addc_u32 s13, s13, 0
	s_cmp_gt_u32 s96, 13
	s_cbranch_scc0 .LBB0_72
	s_and_b64 vcc, exec, s[10:11]
	s_cbranch_vccz .LBB0_75
	s_barrier

.LBB0_198:
	s_add_u32 s12, s0, 0xfffc0080
	s_addc_u32 s13, s1, -1
	s_add_i32 vcc_lo, 0, 0x10000
	s_cmp_eq_u32 s45, 12
	s_cselect_b32 s15, s7, s13
	s_cselect_b32 s14, s23, s12
	v_add_u32_e32 v2, vcc_lo, v200
	s_cselect_b32 s13, s5, s44
	s_cselect_b32 s12, s42, s43
	s_add_i32 s24, 0, 0x14000
	ds_read_b128 v[20:23], v2
	ds_read_b128 v[24:27], v2 offset:1024
	ds_read_b128 v[36:39], v2 offset:2048
	ds_read_b128 v[40:43], v2 offset:3072
	v_add_u32_e32 v2, s24, v200
	ds_read_b128 v[148:151], v2
	ds_read_b128 v[152:155], v2 offset:1024
	ds_read_b128 v[182:185], v2 offset:2048
	ds_read_b128 v[186:189], v2 offset:3072
	v_lshl_add_u64 v[232:233], s[0:1], 0, v[180:181]
	s_add_i32 m0, s63, 0xc000
	ds_read_b128 v[190:193], v202
	ds_read_b128 v[204:207], v202 offset:1024
	ds_read_b128 v[208:211], v202 offset:2048
	ds_read_b128 v[212:215], v202 offset:3072
	ds_read_b128 v[216:219], v202 offset:4096
	ds_read_b128 v[220:223], v202 offset:5120
	ds_read_b128 v[224:227], v202 offset:6144
	ds_read_b128 v[228:231], v202 offset:7168
	global_load_lds_dwordx4 v[232:233], off
	v_lshl_add_u64 v[232:233], s[0:1], 0, v[178:179]
	s_add_i32 m0, s63, 0xe000
	s_nop 0
	global_load_lds_dwordx4 v[232:233], off
	s_waitcnt vmcnt(8)
	s_waitcnt lgkmcnt(0)
	s_barrier
	s_setprio 1
	v_mfma_f32_16x16x32_bf16 v[144:147], v[20:23], v[190:193], v[144:147]
	v_mfma_f32_16x16x32_bf16 v[140:143], v[36:39], v[190:193], v[140:143]
	v_mfma_f32_16x16x32_bf16 v[128:131], v[20:23], v[208:211], v[128:131]
	v_mfma_f32_16x16x32_bf16 v[124:127], v[36:39], v[208:211], v[124:127]
	v_mfma_f32_16x16x32_bf16 v[112:115], v[20:23], v[216:219], v[112:115]
	v_mfma_f32_16x16x32_bf16 v[108:111], v[36:39], v[216:219], v[108:111]
	v_mfma_f32_16x16x32_bf16 v[96:99], v[20:23], v[224:227], v[96:99]
	v_mfma_f32_16x16x32_bf16 v[92:95], v[36:39], v[224:227], v[92:95]
	v_mfma_f32_16x16x32_bf16 v[144:147], v[24:27], v[204:207], v[144:147]
	v_mfma_f32_16x16x32_bf16 v[140:143], v[40:43], v[204:207], v[140:143]
	v_mfma_f32_16x16x32_bf16 v[128:131], v[24:27], v[212:215], v[128:131]
	v_mfma_f32_16x16x32_bf16 v[124:127], v[40:43], v[212:215], v[124:127]
	v_mfma_f32_16x16x32_bf16 v[112:115], v[24:27], v[220:223], v[112:115]
	v_mfma_f32_16x16x32_bf16 v[108:111], v[40:43], v[220:223], v[108:111]
	v_mfma_f32_16x16x32_bf16 v[96:99], v[24:27], v[228:231], v[96:99]
	v_mfma_f32_16x16x32_bf16 v[92:95], v[40:43], v[228:231], v[92:95]
	v_mfma_f32_16x16x32_bf16 v[136:139], v[148:151], v[190:193], v[136:139]
	v_mfma_f32_16x16x32_bf16 v[132:135], v[182:185], v[190:193], v[132:135]
	v_mfma_f32_16x16x32_bf16 v[120:123], v[148:151], v[208:211], v[120:123]
	v_mfma_f32_16x16x32_bf16 v[116:119], v[182:185], v[208:211], v[116:119]
	v_mfma_f32_16x16x32_bf16 v[104:107], v[148:151], v[216:219], v[104:107]
	v_mfma_f32_16x16x32_bf16 v[100:103], v[182:185], v[216:219], v[100:103]
	v_mfma_f32_16x16x32_bf16 v[88:91], v[148:151], v[224:227], v[88:91]
	v_mfma_f32_16x16x32_bf16 v[84:87], v[182:185], v[224:227], v[84:87]
	v_mfma_f32_16x16x32_bf16 v[136:139], v[152:155], v[204:207], v[136:139]
	v_mfma_f32_16x16x32_bf16 v[132:135], v[186:189], v[204:207], v[132:135]
	v_mfma_f32_16x16x32_bf16 v[120:123], v[152:155], v[212:215], v[120:123]
	v_mfma_f32_16x16x32_bf16 v[116:119], v[186:189], v[212:215], v[116:119]
	v_mfma_f32_16x16x32_bf16 v[104:107], v[152:155], v[220:223], v[104:107]
	v_mfma_f32_16x16x32_bf16 v[100:103], v[186:189], v[220:223], v[100:103]
	v_mfma_f32_16x16x32_bf16 v[88:91], v[152:155], v[228:231], v[88:91]
	v_mfma_f32_16x16x32_bf16 v[84:87], v[186:189], v[228:231], v[84:87]
	s_setprio 0
	s_barrier
	s_add_i32 s25, vcc_lo, s89
	v_lshl_add_u64 v[232:233], s[12:13], 0, v[174:175]
	s_mov_b32 m0, s25
	ds_read_b128 v[190:193], v202 offset:16384
	ds_read_b128 v[204:207], v202 offset:17408
	ds_read_b128 v[208:211], v202 offset:18432
	ds_read_b128 v[212:215], v202 offset:19456
	ds_read_b128 v[216:219], v202 offset:20480
	ds_read_b128 v[220:223], v202 offset:21504
	ds_read_b128 v[224:227], v202 offset:22528
	ds_read_b128 v[228:231], v202 offset:23552
	global_load_lds_dwordx4 v[232:233], off
	s_add_i32 m0, s25, 0x2000
	s_add_u32 vcc_lo, s12, 0x40000
	v_lshl_add_u64 v[234:235], s[12:13], 0, v[0:1]
	s_addc_u32 vcc_hi, s13, 0
	s_add_i32 s24, s24, s89
	global_load_lds_dwordx4 v[234:235], off
	v_lshl_add_u64 v[236:237], vcc, 0, v[174:175]
	s_mov_b32 m0, s24
	v_lshl_add_u64 v[238:239], s[14:15], 0, v[172:173]
	global_load_lds_dwordx4 v[236:237], off
	v_lshl_add_u64 v[236:237], vcc, 0, v[0:1]
	s_add_i32 m0, s24, 0x2000
	s_nop 0
	global_load_lds_dwordx4 v[236:237], off
	v_lshl_add_u64 v[236:237], s[14:15], 0, v[176:177]
	s_mov_b32 m0, s63
	s_nop 0
	global_load_lds_dwordx4 v[236:237], off
	s_mov_b32 m0, s87
	s_nop 0
	global_load_lds_dwordx4 v[238:239], off
	s_waitcnt vmcnt(8)
	s_waitcnt lgkmcnt(0)
	s_barrier
	s_setprio 1
	v_mfma_f32_16x16x32_bf16 v[80:83], v[20:23], v[190:193], v[80:83]
	v_mfma_f32_16x16x32_bf16 v[76:79], v[36:39], v[190:193], v[76:79]
	v_mfma_f32_16x16x32_bf16 v[64:67], v[20:23], v[208:211], v[64:67]
	v_mfma_f32_16x16x32_bf16 v[60:63], v[36:39], v[208:211], v[60:63]
	v_mfma_f32_16x16x32_bf16 v[48:51], v[20:23], v[216:219], v[48:51]
	v_mfma_f32_16x16x32_bf16 v[44:47], v[36:39], v[216:219], v[44:47]
	v_mfma_f32_16x16x32_bf16 v[16:19], v[20:23], v[224:227], v[16:19]
	v_mfma_f32_16x16x32_bf16 v[12:15], v[36:39], v[224:227], v[12:15]
	v_mfma_f32_16x16x32_bf16 v[80:83], v[24:27], v[204:207], v[80:83]
	v_mfma_f32_16x16x32_bf16 v[76:79], v[40:43], v[204:207], v[76:79]
	v_mfma_f32_16x16x32_bf16 v[64:67], v[24:27], v[212:215], v[64:67]
	v_mfma_f32_16x16x32_bf16 v[60:63], v[40:43], v[212:215], v[60:63]
	v_mfma_f32_16x16x32_bf16 v[48:51], v[24:27], v[220:223], v[48:51]
	v_mfma_f32_16x16x32_bf16 v[44:47], v[40:43], v[220:223], v[44:47]
	v_mfma_f32_16x16x32_bf16 v[16:19], v[24:27], v[228:231], v[16:19]
	v_mfma_f32_16x16x32_bf16 v[12:15], v[40:43], v[228:231], v[12:15]
	v_mfma_f32_16x16x32_bf16 v[32:35], v[148:151], v[216:219], v[32:35]
	v_mfma_f32_16x16x32_bf16 v[28:31], v[182:185], v[216:219], v[28:31]
	v_mfma_f32_16x16x32_bf16 v[8:11], v[148:151], v[224:227], v[8:11]
	v_mfma_f32_16x16x32_bf16 v[4:7], v[182:185], v[224:227], v[4:7]
	v_mfma_f32_16x16x32_bf16 v[20:23], v[148:151], v[190:193], v[72:75]
	v_mfma_f32_16x16x32_bf16 v[24:27], v[182:185], v[190:193], v[68:71]
	v_mfma_f32_16x16x32_bf16 v[36:39], v[148:151], v[208:211], v[56:59]
	v_mfma_f32_16x16x32_bf16 v[40:43], v[182:185], v[208:211], v[52:55]
	v_mfma_f32_16x16x32_bf16 v[32:35], v[152:155], v[220:223], v[32:35]
	v_mfma_f32_16x16x32_bf16 v[28:31], v[186:189], v[220:223], v[28:31]
	v_mfma_f32_16x16x32_bf16 v[8:11], v[152:155], v[228:231], v[8:11]
	v_mfma_f32_16x16x32_bf16 v[4:7], v[186:189], v[228:231], v[4:7]
	v_mfma_f32_16x16x32_bf16 v[20:23], v[152:155], v[204:207], v[20:23]
	v_mfma_f32_16x16x32_bf16 v[24:27], v[186:189], v[204:207], v[24:27]
	v_mfma_f32_16x16x32_bf16 v[36:39], v[152:155], v[212:215], v[36:39]
	v_mfma_f32_16x16x32_bf16 v[40:43], v[186:189], v[212:215], v[40:43]
	s_setprio 0
	s_barrier
	s_add_i32 s24, 0, 0x18000
	v_add_u32_e32 v2, s24, v200
	s_add_i32 s25, 0, 0x1c000
	ds_read_b128 v[52:55], v2
	ds_read_b128 v[56:59], v2 offset:1024
	ds_read_b128 v[68:71], v2 offset:2048
	ds_read_b128 v[72:75], v2 offset:3072
	v_add_u32_e32 v2, s25, v200
	ds_read_b128 v[148:151], v2
	ds_read_b128 v[152:155], v2 offset:1024
	ds_read_b128 v[182:185], v2 offset:2048
	ds_read_b128 v[186:189], v2 offset:3072
	s_add_u32 s14, s14, 0x40000
	s_addc_u32 s15, s15, 0
	s_mov_b32 m0, s18
	v_lshl_add_u64 v[240:241], s[14:15], 0, v[176:177]
	ds_read_b128 v[190:193], v202 offset:32768
	ds_read_b128 v[204:207], v202 offset:33792
	ds_read_b128 v[208:211], v202 offset:34816
	ds_read_b128 v[212:215], v202 offset:35840
	ds_read_b128 v[216:219], v202 offset:36864
	ds_read_b128 v[220:223], v202 offset:37888
	ds_read_b128 v[224:227], v202 offset:38912
	ds_read_b128 v[228:231], v202 offset:39936
	global_load_lds_dwordx4 v[240:241], off
	v_lshl_add_u64 v[240:241], s[14:15], 0, v[172:173]
	s_mov_b32 m0, s19
	s_nop 0
	global_load_lds_dwordx4 v[240:241], off
	s_waitcnt vmcnt(8)
	s_waitcnt lgkmcnt(0)
	s_barrier
	s_setprio 1
	v_mfma_f32_16x16x32_bf16 v[144:147], v[52:55], v[190:193], v[144:147]
	v_mfma_f32_16x16x32_bf16 v[140:143], v[68:71], v[190:193], v[140:143]
	v_mfma_f32_16x16x32_bf16 v[128:131], v[52:55], v[208:211], v[128:131]
	v_mfma_f32_16x16x32_bf16 v[124:127], v[68:71], v[208:211], v[124:127]
	v_mfma_f32_16x16x32_bf16 v[112:115], v[52:55], v[216:219], v[112:115]
	v_mfma_f32_16x16x32_bf16 v[108:111], v[68:71], v[216:219], v[108:111]
	v_mfma_f32_16x16x32_bf16 v[96:99], v[52:55], v[224:227], v[96:99]
	v_mfma_f32_16x16x32_bf16 v[92:95], v[68:71], v[224:227], v[92:95]
	v_mfma_f32_16x16x32_bf16 v[144:147], v[56:59], v[204:207], v[144:147]
	v_mfma_f32_16x16x32_bf16 v[140:143], v[72:75], v[204:207], v[140:143]
	v_mfma_f32_16x16x32_bf16 v[128:131], v[56:59], v[212:215], v[128:131]
	v_mfma_f32_16x16x32_bf16 v[124:127], v[72:75], v[212:215], v[124:127]
	v_mfma_f32_16x16x32_bf16 v[112:115], v[56:59], v[220:223], v[112:115]
	v_mfma_f32_16x16x32_bf16 v[108:111], v[72:75], v[220:223], v[108:111]
	v_mfma_f32_16x16x32_bf16 v[96:99], v[56:59], v[228:231], v[96:99]
	v_mfma_f32_16x16x32_bf16 v[92:95], v[72:75], v[228:231], v[92:95]
	v_mfma_f32_16x16x32_bf16 v[136:139], v[148:151], v[190:193], v[136:139]
	v_mfma_f32_16x16x32_bf16 v[132:135], v[182:185], v[190:193], v[132:135]
	v_mfma_f32_16x16x32_bf16 v[120:123], v[148:151], v[208:211], v[120:123]
	v_mfma_f32_16x16x32_bf16 v[116:119], v[182:185], v[208:211], v[116:119]
	v_mfma_f32_16x16x32_bf16 v[104:107], v[148:151], v[216:219], v[104:107]
	v_mfma_f32_16x16x32_bf16 v[100:103], v[182:185], v[216:219], v[100:103]
	v_mfma_f32_16x16x32_bf16 v[88:91], v[148:151], v[224:227], v[88:91]
	v_mfma_f32_16x16x32_bf16 v[84:87], v[182:185], v[224:227], v[84:87]
	v_mfma_f32_16x16x32_bf16 v[136:139], v[152:155], v[204:207], v[136:139]
	v_mfma_f32_16x16x32_bf16 v[132:135], v[186:189], v[204:207], v[132:135]
	v_mfma_f32_16x16x32_bf16 v[120:123], v[152:155], v[212:215], v[120:123]
	v_mfma_f32_16x16x32_bf16 v[116:119], v[186:189], v[212:215], v[116:119]
	v_mfma_f32_16x16x32_bf16 v[104:107], v[152:155], v[220:223], v[104:107]
	v_mfma_f32_16x16x32_bf16 v[100:103], v[186:189], v[220:223], v[100:103]
	v_mfma_f32_16x16x32_bf16 v[88:91], v[152:155], v[228:231], v[88:91]
	v_mfma_f32_16x16x32_bf16 v[84:87], v[186:189], v[228:231], v[84:87]
	s_setprio 0
	s_barrier
	s_add_i32 s14, s24, s89
	v_lshl_add_u64 v[232:233], v[232:233], 0, s[26:27]
	s_mov_b32 m0, s14
	ds_read_b128 v[190:193], v202 offset:49152
	ds_read_b128 v[204:207], v202 offset:50176
	ds_read_b128 v[208:211], v202 offset:51200
	ds_read_b128 v[212:215], v202 offset:52224
	ds_read_b128 v[216:219], v202 offset:53248
	ds_read_b128 v[220:223], v202 offset:54272
	ds_read_b128 v[224:227], v202 offset:55296
	ds_read_b128 v[228:231], v202 offset:56320
	global_load_lds_dwordx4 v[232:233], off
	s_add_i32 m0, s14, 0x2000
	s_add_u32 s12, s12, 0x40080
	v_lshl_add_u64 v[232:233], v[234:235], 0, s[26:27]
	s_addc_u32 s13, s13, 0
	s_add_i32 s14, s25, s89
	global_load_lds_dwordx4 v[232:233], off
	v_lshl_add_u64 v[232:233], s[12:13], 0, v[174:175]
	s_mov_b32 m0, s14
	s_nop 0
	global_load_lds_dwordx4 v[232:233], off
	v_lshl_add_u64 v[232:233], s[12:13], 0, v[0:1]
	s_add_i32 m0, s14, 0x2000
	s_nop 0
	global_load_lds_dwordx4 v[232:233], off
	v_lshl_add_u64 v[232:233], v[236:237], 0, s[26:27]
	s_mov_b32 m0, s20
	s_nop 0
	global_load_lds_dwordx4 v[232:233], off
	v_lshl_add_u64 v[232:233], v[238:239], 0, s[26:27]
	s_mov_b32 m0, s21
	s_nop 0
	global_load_lds_dwordx4 v[232:233], off
	s_waitcnt vmcnt(8)
	s_waitcnt lgkmcnt(0)
	s_barrier
	s_setprio 1
	v_mfma_f32_16x16x32_bf16 v[80:83], v[52:55], v[190:193], v[80:83]
	v_mfma_f32_16x16x32_bf16 v[76:79], v[68:71], v[190:193], v[76:79]
	v_mfma_f32_16x16x32_bf16 v[64:67], v[52:55], v[208:211], v[64:67]
	v_mfma_f32_16x16x32_bf16 v[60:63], v[68:71], v[208:211], v[60:63]
	v_mfma_f32_16x16x32_bf16 v[48:51], v[52:55], v[216:219], v[48:51]
	v_mfma_f32_16x16x32_bf16 v[44:47], v[68:71], v[216:219], v[44:47]
	v_mfma_f32_16x16x32_bf16 v[16:19], v[52:55], v[224:227], v[16:19]
	v_mfma_f32_16x16x32_bf16 v[12:15], v[68:71], v[224:227], v[12:15]
	v_mfma_f32_16x16x32_bf16 v[80:83], v[56:59], v[204:207], v[80:83]
	v_mfma_f32_16x16x32_bf16 v[76:79], v[72:75], v[204:207], v[76:79]
	v_mfma_f32_16x16x32_bf16 v[64:67], v[56:59], v[212:215], v[64:67]
	v_mfma_f32_16x16x32_bf16 v[60:63], v[72:75], v[212:215], v[60:63]
	v_mfma_f32_16x16x32_bf16 v[48:51], v[56:59], v[220:223], v[48:51]
	v_mfma_f32_16x16x32_bf16 v[44:47], v[72:75], v[220:223], v[44:47]
	v_mfma_f32_16x16x32_bf16 v[16:19], v[56:59], v[228:231], v[16:19]
	v_mfma_f32_16x16x32_bf16 v[12:15], v[72:75], v[228:231], v[12:15]
	v_mfma_f32_16x16x32_bf16 v[20:23], v[148:151], v[190:193], v[20:23]
	v_mfma_f32_16x16x32_bf16 v[72:75], v[152:155], v[204:207], v[20:23]
	v_mfma_f32_16x16x32_bf16 v[20:23], v[182:185], v[190:193], v[24:27]
	v_mfma_f32_16x16x32_bf16 v[68:71], v[186:189], v[204:207], v[20:23]
	v_mfma_f32_16x16x32_bf16 v[20:23], v[148:151], v[208:211], v[36:39]
	v_mfma_f32_16x16x32_bf16 v[56:59], v[152:155], v[212:215], v[20:23]
	v_mfma_f32_16x16x32_bf16 v[20:23], v[182:185], v[208:211], v[40:43]
	v_mfma_f32_16x16x32_bf16 v[52:55], v[186:189], v[212:215], v[20:23]
	v_mfma_f32_16x16x32_bf16 v[20:23], v[148:151], v[216:219], v[32:35]
	v_mfma_f32_16x16x32_bf16 v[32:35], v[152:155], v[220:223], v[20:23]
	v_mfma_f32_16x16x32_bf16 v[20:23], v[182:185], v[216:219], v[28:31]
	v_mfma_f32_16x16x32_bf16 v[8:11], v[148:151], v[224:227], v[8:11]
	v_mfma_f32_16x16x32_bf16 v[4:7], v[182:185], v[224:227], v[4:7]
	v_mfma_f32_16x16x32_bf16 v[28:31], v[186:189], v[220:223], v[20:23]
	v_mfma_f32_16x16x32_bf16 v[8:11], v[152:155], v[228:231], v[8:11]
	v_mfma_f32_16x16x32_bf16 v[4:7], v[186:189], v[228:231], v[4:7]
	s_setprio 0
	s_barrier
	s_add_i32 s45, s45, 2
	s_add_u32 s43, s43, 0x100
	s_addc_u32 s44, s44, 0
	s_add_u32 s0, s0, 0x100
	s_addc_u32 s1, s1, 0
	s_cmp_gt_u32 s45, 13
	s_cbranch_scc0 .LBB0_198
	s_and_b64 vcc, exec, s[38:39]
	s_cbranch_vccz .LBB0_201
	s_barrier

.LBB0_493:
	s_add_u32 s14, s44, 0xfffc0080
	s_addc_u32 s15, s45, -1
	s_add_i32 s63, 0, 0x10000
	s_cmp_eq_u32 s61, 12
	s_cselect_b32 s47, s29, s15
	s_cselect_b32 s46, s51, s14
	s_cselect_b32 s15, s13, s60
	s_cselect_b32 s14, s54, s55
	s_add_i32 s76, 0, 0x14000
	v_add_u32_e32 v172, s63, v145
	v_add_u32_e32 v188, s76, v145
	ds_read_b128 v[140:143], v172
	ds_read_b128 v[148:151], v172 offset:1024
	ds_read_b128 v[152:155], v172 offset:2048
	ds_read_b128 v[172:175], v172 offset:3072
	ds_read_b128 v[176:179], v188
	ds_read_b128 v[180:183], v188 offset:1024
	ds_read_b128 v[184:187], v188 offset:2048
	ds_read_b128 v[188:191], v188 offset:3072
	v_lshl_add_u64 v[192:193], s[44:45], 0, v[138:139]
	s_add_i32 m0, s21, 0xc000
	ds_read_b128 v[200:203], v147
	ds_read_b128 v[204:207], v147 offset:1024
	ds_read_b128 v[208:211], v147 offset:2048
	ds_read_b128 v[212:215], v147 offset:3072
	ds_read_b128 v[216:219], v147 offset:4096
	ds_read_b128 v[220:223], v147 offset:5120
	ds_read_b128 v[224:227], v147 offset:6144
	ds_read_b128 v[228:231], v147 offset:7168
	global_load_lds_dwordx4 v[192:193], off
	v_lshl_add_u64 v[192:193], s[44:45], 0, v[136:137]
	s_add_i32 m0, s21, 0xe000
	s_nop 0
	global_load_lds_dwordx4 v[192:193], off
	s_waitcnt vmcnt(8)
	s_waitcnt lgkmcnt(0)
	s_barrier
	s_setprio 1
	v_mfma_f32_16x16x32_bf16 v[128:131], v[140:143], v[200:203], v[128:131]
	v_mfma_f32_16x16x32_bf16 v[124:127], v[152:155], v[200:203], v[124:127]
	v_mfma_f32_16x16x32_bf16 v[112:115], v[140:143], v[208:211], v[112:115]
	v_mfma_f32_16x16x32_bf16 v[108:111], v[152:155], v[208:211], v[108:111]
	v_mfma_f32_16x16x32_bf16 v[96:99], v[140:143], v[216:219], v[96:99]
	v_mfma_f32_16x16x32_bf16 v[92:95], v[152:155], v[216:219], v[92:95]
	v_mfma_f32_16x16x32_bf16 v[80:83], v[140:143], v[224:227], v[80:83]
	v_mfma_f32_16x16x32_bf16 v[76:79], v[152:155], v[224:227], v[76:79]
	v_mfma_f32_16x16x32_bf16 v[128:131], v[148:151], v[204:207], v[128:131]
	v_mfma_f32_16x16x32_bf16 v[124:127], v[172:175], v[204:207], v[124:127]
	v_mfma_f32_16x16x32_bf16 v[112:115], v[148:151], v[212:215], v[112:115]
	v_mfma_f32_16x16x32_bf16 v[108:111], v[172:175], v[212:215], v[108:111]
	v_mfma_f32_16x16x32_bf16 v[96:99], v[148:151], v[220:223], v[96:99]
	v_mfma_f32_16x16x32_bf16 v[92:95], v[172:175], v[220:223], v[92:95]
	v_mfma_f32_16x16x32_bf16 v[80:83], v[148:151], v[228:231], v[80:83]
	v_mfma_f32_16x16x32_bf16 v[76:79], v[172:175], v[228:231], v[76:79]
	v_mfma_f32_16x16x32_bf16 v[120:123], v[176:179], v[200:203], v[120:123]
	v_mfma_f32_16x16x32_bf16 v[116:119], v[184:187], v[200:203], v[116:119]
	v_mfma_f32_16x16x32_bf16 v[104:107], v[176:179], v[208:211], v[104:107]
	v_mfma_f32_16x16x32_bf16 v[100:103], v[184:187], v[208:211], v[100:103]
	v_mfma_f32_16x16x32_bf16 v[88:91], v[176:179], v[216:219], v[88:91]
	v_mfma_f32_16x16x32_bf16 v[84:87], v[184:187], v[216:219], v[84:87]
	v_mfma_f32_16x16x32_bf16 v[72:75], v[176:179], v[224:227], v[72:75]
	v_mfma_f32_16x16x32_bf16 v[68:71], v[184:187], v[224:227], v[68:71]
	v_mfma_f32_16x16x32_bf16 v[120:123], v[180:183], v[204:207], v[120:123]
	v_mfma_f32_16x16x32_bf16 v[116:119], v[188:191], v[204:207], v[116:119]
	v_mfma_f32_16x16x32_bf16 v[104:107], v[180:183], v[212:215], v[104:107]
	v_mfma_f32_16x16x32_bf16 v[100:103], v[188:191], v[212:215], v[100:103]
	v_mfma_f32_16x16x32_bf16 v[88:91], v[180:183], v[220:223], v[88:91]
	v_mfma_f32_16x16x32_bf16 v[84:87], v[188:191], v[220:223], v[84:87]
	v_mfma_f32_16x16x32_bf16 v[72:75], v[180:183], v[228:231], v[72:75]
	v_mfma_f32_16x16x32_bf16 v[68:71], v[188:191], v[228:231], v[68:71]
	s_setprio 0
	s_barrier
	s_add_i32 s63, s63, s20
	v_lshl_add_u64 v[192:193], s[14:15], 0, v[2:3]
	s_mov_b32 m0, s63
	ds_read_b128 v[200:203], v147 offset:16384
	ds_read_b128 v[204:207], v147 offset:17408
	ds_read_b128 v[208:211], v147 offset:18432
	ds_read_b128 v[212:215], v147 offset:19456
	ds_read_b128 v[216:219], v147 offset:20480
	ds_read_b128 v[220:223], v147 offset:21504
	ds_read_b128 v[224:227], v147 offset:22528
	ds_read_b128 v[228:231], v147 offset:23552
	global_load_lds_dwordx4 v[192:193], off
	s_add_i32 m0, s63, 0x2000
	s_add_u32 s64, s14, 0x40000
	v_lshl_add_u64 v[232:233], s[14:15], 0, v[134:135]
	s_addc_u32 s65, s15, 0
	s_add_i32 s63, s76, s20
	global_load_lds_dwordx4 v[232:233], off
	v_lshl_add_u64 v[234:235], s[64:65], 0, v[2:3]
	s_mov_b32 m0, s63
	v_lshl_add_u64 v[236:237], s[46:47], 0, v[132:133]
	global_load_lds_dwordx4 v[234:235], off
	v_lshl_add_u64 v[234:235], s[64:65], 0, v[134:135]
	s_add_i32 m0, s63, 0x2000
	s_nop 0
	global_load_lds_dwordx4 v[234:235], off
	v_lshl_add_u64 v[234:235], s[46:47], 0, v[0:1]
	s_mov_b32 m0, s21
	s_nop 0
	global_load_lds_dwordx4 v[234:235], off
	s_mov_b32 m0, s22
	s_nop 0
	global_load_lds_dwordx4 v[236:237], off
	s_waitcnt vmcnt(8)
	s_waitcnt lgkmcnt(0)
	s_barrier
	s_setprio 1
	v_mfma_f32_16x16x32_bf16 v[64:67], v[140:143], v[200:203], v[64:67]
	v_mfma_f32_16x16x32_bf16 v[60:63], v[152:155], v[200:203], v[60:63]
	v_mfma_f32_16x16x32_bf16 v[48:51], v[140:143], v[208:211], v[48:51]
	v_mfma_f32_16x16x32_bf16 v[44:47], v[152:155], v[208:211], v[44:47]
	v_mfma_f32_16x16x32_bf16 v[32:35], v[140:143], v[216:219], v[32:35]
	v_mfma_f32_16x16x32_bf16 v[28:31], v[152:155], v[216:219], v[28:31]
	v_mfma_f32_16x16x32_bf16 v[16:19], v[140:143], v[224:227], v[16:19]
	v_mfma_f32_16x16x32_bf16 v[12:15], v[152:155], v[224:227], v[12:15]
	v_mfma_f32_16x16x32_bf16 v[64:67], v[148:151], v[204:207], v[64:67]
	v_mfma_f32_16x16x32_bf16 v[60:63], v[172:175], v[204:207], v[60:63]
	v_mfma_f32_16x16x32_bf16 v[48:51], v[148:151], v[212:215], v[48:51]
	v_mfma_f32_16x16x32_bf16 v[44:47], v[172:175], v[212:215], v[44:47]
	v_mfma_f32_16x16x32_bf16 v[32:35], v[148:151], v[220:223], v[32:35]
	v_mfma_f32_16x16x32_bf16 v[28:31], v[172:175], v[220:223], v[28:31]
	v_mfma_f32_16x16x32_bf16 v[16:19], v[148:151], v[228:231], v[16:19]
	v_mfma_f32_16x16x32_bf16 v[12:15], v[172:175], v[228:231], v[12:15]
	v_mfma_f32_16x16x32_bf16 v[56:59], v[176:179], v[200:203], v[56:59]
	v_mfma_f32_16x16x32_bf16 v[52:55], v[184:187], v[200:203], v[52:55]
	v_mfma_f32_16x16x32_bf16 v[40:43], v[176:179], v[208:211], v[40:43]
	v_mfma_f32_16x16x32_bf16 v[36:39], v[184:187], v[208:211], v[36:39]
	v_mfma_f32_16x16x32_bf16 v[24:27], v[176:179], v[216:219], v[24:27]
	v_mfma_f32_16x16x32_bf16 v[20:23], v[184:187], v[216:219], v[20:23]
	v_mfma_f32_16x16x32_bf16 v[8:11], v[176:179], v[224:227], v[8:11]
	v_mfma_f32_16x16x32_bf16 v[4:7], v[184:187], v[224:227], v[4:7]
	v_mfma_f32_16x16x32_bf16 v[56:59], v[180:183], v[204:207], v[56:59]
	v_mfma_f32_16x16x32_bf16 v[52:55], v[188:191], v[204:207], v[52:55]
	v_mfma_f32_16x16x32_bf16 v[40:43], v[180:183], v[212:215], v[40:43]
	v_mfma_f32_16x16x32_bf16 v[36:39], v[188:191], v[212:215], v[36:39]
	v_mfma_f32_16x16x32_bf16 v[24:27], v[180:183], v[220:223], v[24:27]
	v_mfma_f32_16x16x32_bf16 v[20:23], v[188:191], v[220:223], v[20:23]
	v_mfma_f32_16x16x32_bf16 v[8:11], v[180:183], v[228:231], v[8:11]
	v_mfma_f32_16x16x32_bf16 v[4:7], v[188:191], v[228:231], v[4:7]
	s_setprio 0
	s_barrier
	s_add_i32 s63, 0, 0x18000
	s_add_i32 s64, 0, 0x1c000
	v_add_u32_e32 v172, s63, v145
	v_add_u32_e32 v188, s64, v145
	ds_read_b128 v[140:143], v172
	ds_read_b128 v[148:151], v172 offset:1024
	ds_read_b128 v[152:155], v172 offset:2048
	ds_read_b128 v[172:175], v172 offset:3072
	ds_read_b128 v[176:179], v188
	ds_read_b128 v[180:183], v188 offset:1024
	ds_read_b128 v[184:187], v188 offset:2048
	ds_read_b128 v[188:191], v188 offset:3072
	s_add_u32 s46, s46, 0x40000
	s_addc_u32 s47, s47, 0
	s_mov_b32 m0, s23
	v_lshl_add_u64 v[238:239], s[46:47], 0, v[0:1]
	ds_read_b128 v[200:203], v147 offset:32768
	ds_read_b128 v[204:207], v147 offset:33792
	ds_read_b128 v[208:211], v147 offset:34816
	ds_read_b128 v[212:215], v147 offset:35840
	ds_read_b128 v[216:219], v147 offset:36864
	ds_read_b128 v[220:223], v147 offset:37888
	ds_read_b128 v[224:227], v147 offset:38912
	ds_read_b128 v[228:231], v147 offset:39936
	global_load_lds_dwordx4 v[238:239], off
	v_lshl_add_u64 v[238:239], s[46:47], 0, v[132:133]
	s_mov_b32 m0, s36
	s_nop 0
	global_load_lds_dwordx4 v[238:239], off
	s_waitcnt vmcnt(8)
	s_waitcnt lgkmcnt(0)
	s_barrier
	s_setprio 1
	v_mfma_f32_16x16x32_bf16 v[128:131], v[140:143], v[200:203], v[128:131]
	v_mfma_f32_16x16x32_bf16 v[124:127], v[152:155], v[200:203], v[124:127]
	v_mfma_f32_16x16x32_bf16 v[112:115], v[140:143], v[208:211], v[112:115]
	v_mfma_f32_16x16x32_bf16 v[108:111], v[152:155], v[208:211], v[108:111]
	v_mfma_f32_16x16x32_bf16 v[96:99], v[140:143], v[216:219], v[96:99]
	v_mfma_f32_16x16x32_bf16 v[92:95], v[152:155], v[216:219], v[92:95]
	v_mfma_f32_16x16x32_bf16 v[80:83], v[140:143], v[224:227], v[80:83]
	v_mfma_f32_16x16x32_bf16 v[76:79], v[152:155], v[224:227], v[76:79]
	v_mfma_f32_16x16x32_bf16 v[128:131], v[148:151], v[204:207], v[128:131]
	v_mfma_f32_16x16x32_bf16 v[124:127], v[172:175], v[204:207], v[124:127]
	v_mfma_f32_16x16x32_bf16 v[112:115], v[148:151], v[212:215], v[112:115]
	v_mfma_f32_16x16x32_bf16 v[108:111], v[172:175], v[212:215], v[108:111]
	v_mfma_f32_16x16x32_bf16 v[96:99], v[148:151], v[220:223], v[96:99]
	v_mfma_f32_16x16x32_bf16 v[92:95], v[172:175], v[220:223], v[92:95]
	v_mfma_f32_16x16x32_bf16 v[80:83], v[148:151], v[228:231], v[80:83]
	v_mfma_f32_16x16x32_bf16 v[76:79], v[172:175], v[228:231], v[76:79]
	v_mfma_f32_16x16x32_bf16 v[120:123], v[176:179], v[200:203], v[120:123]
	v_mfma_f32_16x16x32_bf16 v[116:119], v[184:187], v[200:203], v[116:119]
	v_mfma_f32_16x16x32_bf16 v[104:107], v[176:179], v[208:211], v[104:107]
	v_mfma_f32_16x16x32_bf16 v[100:103], v[184:187], v[208:211], v[100:103]
	v_mfma_f32_16x16x32_bf16 v[88:91], v[176:179], v[216:219], v[88:91]
	v_mfma_f32_16x16x32_bf16 v[84:87], v[184:187], v[216:219], v[84:87]
	v_mfma_f32_16x16x32_bf16 v[72:75], v[176:179], v[224:227], v[72:75]
	v_mfma_f32_16x16x32_bf16 v[68:71], v[184:187], v[224:227], v[68:71]
	v_mfma_f32_16x16x32_bf16 v[120:123], v[180:183], v[204:207], v[120:123]
	v_mfma_f32_16x16x32_bf16 v[116:119], v[188:191], v[204:207], v[116:119]
	v_mfma_f32_16x16x32_bf16 v[104:107], v[180:183], v[212:215], v[104:107]
	v_mfma_f32_16x16x32_bf16 v[100:103], v[188:191], v[212:215], v[100:103]
	v_mfma_f32_16x16x32_bf16 v[88:91], v[180:183], v[220:223], v[88:91]
	v_mfma_f32_16x16x32_bf16 v[84:87], v[188:191], v[220:223], v[84:87]
	v_mfma_f32_16x16x32_bf16 v[72:75], v[180:183], v[228:231], v[72:75]
	v_mfma_f32_16x16x32_bf16 v[68:71], v[188:191], v[228:231], v[68:71]
	s_setprio 0
	s_barrier
	s_add_i32 s46, s63, s20
	v_lshl_add_u64 v[192:193], v[192:193], 0, s[26:27]
	s_mov_b32 m0, s46
	ds_read_b128 v[200:203], v147 offset:49152
	ds_read_b128 v[204:207], v147 offset:50176
	ds_read_b128 v[208:211], v147 offset:51200
	ds_read_b128 v[212:215], v147 offset:52224
	ds_read_b128 v[216:219], v147 offset:53248
	ds_read_b128 v[220:223], v147 offset:54272
	ds_read_b128 v[224:227], v147 offset:55296
	ds_read_b128 v[228:231], v147 offset:56320
	global_load_lds_dwordx4 v[192:193], off
	s_add_i32 m0, s46, 0x2000
	s_add_u32 s14, s14, 0x40080
	v_lshl_add_u64 v[192:193], v[232:233], 0, s[26:27]
	s_addc_u32 s15, s15, 0
	s_add_i32 s46, s64, s20
	global_load_lds_dwordx4 v[192:193], off
	v_lshl_add_u64 v[192:193], s[14:15], 0, v[2:3]
	s_mov_b32 m0, s46
	s_nop 0
	global_load_lds_dwordx4 v[192:193], off
	v_lshl_add_u64 v[192:193], s[14:15], 0, v[134:135]
	s_add_i32 m0, s46, 0x2000
	s_nop 0
	global_load_lds_dwordx4 v[192:193], off
	v_lshl_add_u64 v[192:193], v[234:235], 0, s[26:27]
	s_mov_b32 m0, s43
	s_nop 0
	global_load_lds_dwordx4 v[192:193], off
	v_lshl_add_u64 v[192:193], v[236:237], 0, s[26:27]
	s_mov_b32 m0, s48
	s_nop 0
	global_load_lds_dwordx4 v[192:193], off
	s_waitcnt vmcnt(8)
	s_waitcnt lgkmcnt(0)
	s_barrier
	s_setprio 1
	v_mfma_f32_16x16x32_bf16 v[64:67], v[140:143], v[200:203], v[64:67]
	v_mfma_f32_16x16x32_bf16 v[60:63], v[152:155], v[200:203], v[60:63]
	v_mfma_f32_16x16x32_bf16 v[48:51], v[140:143], v[208:211], v[48:51]
	v_mfma_f32_16x16x32_bf16 v[44:47], v[152:155], v[208:211], v[44:47]
	v_mfma_f32_16x16x32_bf16 v[32:35], v[140:143], v[216:219], v[32:35]
	v_mfma_f32_16x16x32_bf16 v[28:31], v[152:155], v[216:219], v[28:31]
	v_mfma_f32_16x16x32_bf16 v[16:19], v[140:143], v[224:227], v[16:19]
	v_mfma_f32_16x16x32_bf16 v[12:15], v[152:155], v[224:227], v[12:15]
	v_mfma_f32_16x16x32_bf16 v[64:67], v[148:151], v[204:207], v[64:67]
	v_mfma_f32_16x16x32_bf16 v[60:63], v[172:175], v[204:207], v[60:63]
	v_mfma_f32_16x16x32_bf16 v[48:51], v[148:151], v[212:215], v[48:51]
	v_mfma_f32_16x16x32_bf16 v[44:47], v[172:175], v[212:215], v[44:47]
	v_mfma_f32_16x16x32_bf16 v[32:35], v[148:151], v[220:223], v[32:35]
	v_mfma_f32_16x16x32_bf16 v[28:31], v[172:175], v[220:223], v[28:31]
	v_mfma_f32_16x16x32_bf16 v[16:19], v[148:151], v[228:231], v[16:19]
	v_mfma_f32_16x16x32_bf16 v[12:15], v[172:175], v[228:231], v[12:15]
	v_mfma_f32_16x16x32_bf16 v[56:59], v[176:179], v[200:203], v[56:59]
	v_mfma_f32_16x16x32_bf16 v[52:55], v[184:187], v[200:203], v[52:55]
	v_mfma_f32_16x16x32_bf16 v[40:43], v[176:179], v[208:211], v[40:43]
	v_mfma_f32_16x16x32_bf16 v[36:39], v[184:187], v[208:211], v[36:39]
	v_mfma_f32_16x16x32_bf16 v[24:27], v[176:179], v[216:219], v[24:27]
	v_mfma_f32_16x16x32_bf16 v[20:23], v[184:187], v[216:219], v[20:23]
	v_mfma_f32_16x16x32_bf16 v[8:11], v[176:179], v[224:227], v[8:11]
	v_mfma_f32_16x16x32_bf16 v[4:7], v[184:187], v[224:227], v[4:7]
	v_mfma_f32_16x16x32_bf16 v[56:59], v[180:183], v[204:207], v[56:59]
	v_mfma_f32_16x16x32_bf16 v[52:55], v[188:191], v[204:207], v[52:55]
	v_mfma_f32_16x16x32_bf16 v[40:43], v[180:183], v[212:215], v[40:43]
	v_mfma_f32_16x16x32_bf16 v[36:39], v[188:191], v[212:215], v[36:39]
	v_mfma_f32_16x16x32_bf16 v[24:27], v[180:183], v[220:223], v[24:27]
	v_mfma_f32_16x16x32_bf16 v[20:23], v[188:191], v[220:223], v[20:23]
	v_mfma_f32_16x16x32_bf16 v[8:11], v[180:183], v[228:231], v[8:11]
	v_mfma_f32_16x16x32_bf16 v[4:7], v[188:191], v[228:231], v[4:7]
	s_setprio 0
	s_barrier
	s_add_i32 s61, s61, 2
	s_add_u32 s55, s55, 0x100
	s_addc_u32 s60, s60, 0
	s_add_u32 s44, s44, 0x100
	s_addc_u32 s45, s45, 0
	s_cmp_gt_u32 s61, 13
	s_cbranch_scc0 .LBB0_493
	s_and_b64 vcc, exec, s[10:11]
	s_cbranch_vccz .LBB0_496
	s_barrier

.LBB0_812:
	s_add_u32 s14, s42, 0xfffc0080
	s_addc_u32 s15, s43, -1
	s_add_i32 s24, 0, 0x10000
	s_cmp_eq_u32 s91, 12
	s_cselect_b32 s55, s16, s15
	s_cselect_b32 s54, s17, s14
	s_cselect_b32 s15, s39, s89
	s_cselect_b32 s14, s47, s87
	s_add_i32 s25, 0, 0x14000
	v_add_u32_e32 v152, s24, v175
	v_add_u32_e32 v172, s25, v175
	ds_read_b128 v[132:135], v152
	ds_read_b128 v[136:139], v152 offset:1024
	ds_read_b128 v[148:151], v152 offset:2048
	ds_read_b128 v[152:155], v152 offset:3072
	ds_read_b128 v[178:181], v172
	ds_read_b128 v[182:185], v172 offset:1024
	ds_read_b128 v[186:189], v172 offset:2048
	ds_read_b128 v[190:193], v172 offset:3072
	v_lshl_add_u64 v[172:173], s[42:43], 0, v[146:147]
	s_add_i32 m0, s23, 0xc000
	ds_read_b128 v[200:203], v177
	ds_read_b128 v[204:207], v177 offset:1024
	ds_read_b128 v[208:211], v177 offset:2048
	ds_read_b128 v[212:215], v177 offset:3072
	ds_read_b128 v[216:219], v177 offset:4096
	ds_read_b128 v[220:223], v177 offset:5120
	ds_read_b128 v[224:227], v177 offset:6144
	ds_read_b128 v[228:231], v177 offset:7168
	global_load_lds_dwordx4 v[172:173], off
	v_lshl_add_u64 v[172:173], s[42:43], 0, v[144:145]
	s_add_i32 m0, s23, 0xe000
	s_nop 0
	global_load_lds_dwordx4 v[172:173], off
	s_waitcnt vmcnt(8)
	s_waitcnt lgkmcnt(0)
	s_barrier
	s_setprio 1
	v_mfma_f32_16x16x32_bf16 v[128:131], v[132:135], v[200:203], v[128:131]
	v_mfma_f32_16x16x32_bf16 v[124:127], v[148:151], v[200:203], v[124:127]
	v_mfma_f32_16x16x32_bf16 v[112:115], v[132:135], v[208:211], v[112:115]
	v_mfma_f32_16x16x32_bf16 v[108:111], v[148:151], v[208:211], v[108:111]
	v_mfma_f32_16x16x32_bf16 v[96:99], v[132:135], v[216:219], v[96:99]
	v_mfma_f32_16x16x32_bf16 v[92:95], v[148:151], v[216:219], v[92:95]
	v_mfma_f32_16x16x32_bf16 v[80:83], v[132:135], v[224:227], v[80:83]
	v_mfma_f32_16x16x32_bf16 v[76:79], v[148:151], v[224:227], v[76:79]
	v_mfma_f32_16x16x32_bf16 v[128:131], v[136:139], v[204:207], v[128:131]
	v_mfma_f32_16x16x32_bf16 v[124:127], v[152:155], v[204:207], v[124:127]
	v_mfma_f32_16x16x32_bf16 v[112:115], v[136:139], v[212:215], v[112:115]
	v_mfma_f32_16x16x32_bf16 v[108:111], v[152:155], v[212:215], v[108:111]
	v_mfma_f32_16x16x32_bf16 v[96:99], v[136:139], v[220:223], v[96:99]
	v_mfma_f32_16x16x32_bf16 v[92:95], v[152:155], v[220:223], v[92:95]
	v_mfma_f32_16x16x32_bf16 v[80:83], v[136:139], v[228:231], v[80:83]
	v_mfma_f32_16x16x32_bf16 v[76:79], v[152:155], v[228:231], v[76:79]
	v_mfma_f32_16x16x32_bf16 v[120:123], v[178:181], v[200:203], v[120:123]
	v_mfma_f32_16x16x32_bf16 v[116:119], v[186:189], v[200:203], v[116:119]
	v_mfma_f32_16x16x32_bf16 v[104:107], v[178:181], v[208:211], v[104:107]
	v_mfma_f32_16x16x32_bf16 v[100:103], v[186:189], v[208:211], v[100:103]
	v_mfma_f32_16x16x32_bf16 v[88:91], v[178:181], v[216:219], v[88:91]
	v_mfma_f32_16x16x32_bf16 v[84:87], v[186:189], v[216:219], v[84:87]
	v_mfma_f32_16x16x32_bf16 v[72:75], v[178:181], v[224:227], v[72:75]
	v_mfma_f32_16x16x32_bf16 v[68:71], v[186:189], v[224:227], v[68:71]
	v_mfma_f32_16x16x32_bf16 v[120:123], v[182:185], v[204:207], v[120:123]
	v_mfma_f32_16x16x32_bf16 v[116:119], v[190:193], v[204:207], v[116:119]
	v_mfma_f32_16x16x32_bf16 v[104:107], v[182:185], v[212:215], v[104:107]
	v_mfma_f32_16x16x32_bf16 v[100:103], v[190:193], v[212:215], v[100:103]
	v_mfma_f32_16x16x32_bf16 v[88:91], v[182:185], v[220:223], v[88:91]
	v_mfma_f32_16x16x32_bf16 v[84:87], v[190:193], v[220:223], v[84:87]
	v_mfma_f32_16x16x32_bf16 v[72:75], v[182:185], v[228:231], v[72:75]
	v_mfma_f32_16x16x32_bf16 v[68:71], v[190:193], v[228:231], v[68:71]
	s_setprio 0
	s_barrier
	s_add_i32 s24, s24, s22
	v_lshl_add_u64 v[172:173], s[14:15], 0, v[2:3]
	s_mov_b32 m0, s24
	ds_read_b128 v[200:203], v177 offset:16384
	ds_read_b128 v[204:207], v177 offset:17408
	ds_read_b128 v[208:211], v177 offset:18432
	ds_read_b128 v[212:215], v177 offset:19456
	ds_read_b128 v[216:219], v177 offset:20480
	ds_read_b128 v[220:223], v177 offset:21504
	ds_read_b128 v[224:227], v177 offset:22528
	ds_read_b128 v[228:231], v177 offset:23552
	global_load_lds_dwordx4 v[172:173], off
	s_add_i32 m0, s24, 0x2000
	s_add_u32 s96, s14, 0x40000
	v_lshl_add_u64 v[232:233], s[14:15], 0, v[0:1]
	s_addc_u32 s97, s15, 0
	s_add_i32 s24, s25, s22
	global_load_lds_dwordx4 v[232:233], off
	v_lshl_add_u64 v[234:235], s[96:97], 0, v[2:3]
	s_mov_b32 m0, s24
	v_lshl_add_u64 v[236:237], s[54:55], 0, v[140:141]
	global_load_lds_dwordx4 v[234:235], off
	v_lshl_add_u64 v[234:235], s[96:97], 0, v[0:1]
	s_add_i32 m0, s24, 0x2000
	s_nop 0
	global_load_lds_dwordx4 v[234:235], off
	v_lshl_add_u64 v[234:235], s[54:55], 0, v[142:143]
	s_mov_b32 m0, s23
	s_nop 0
	global_load_lds_dwordx4 v[234:235], off
	s_mov_b32 m0, s45
	s_nop 0
	global_load_lds_dwordx4 v[236:237], off
	s_waitcnt vmcnt(8)
	s_waitcnt lgkmcnt(0)
	s_barrier
	s_setprio 1
	v_mfma_f32_16x16x32_bf16 v[64:67], v[132:135], v[200:203], v[64:67]
	v_mfma_f32_16x16x32_bf16 v[60:63], v[148:151], v[200:203], v[60:63]
	v_mfma_f32_16x16x32_bf16 v[48:51], v[132:135], v[208:211], v[48:51]
	v_mfma_f32_16x16x32_bf16 v[44:47], v[148:151], v[208:211], v[44:47]
	v_mfma_f32_16x16x32_bf16 v[32:35], v[132:135], v[216:219], v[32:35]
	v_mfma_f32_16x16x32_bf16 v[28:31], v[148:151], v[216:219], v[28:31]
	v_mfma_f32_16x16x32_bf16 v[16:19], v[132:135], v[224:227], v[16:19]
	v_mfma_f32_16x16x32_bf16 v[12:15], v[148:151], v[224:227], v[12:15]
	v_mfma_f32_16x16x32_bf16 v[64:67], v[136:139], v[204:207], v[64:67]
	v_mfma_f32_16x16x32_bf16 v[60:63], v[152:155], v[204:207], v[60:63]
	v_mfma_f32_16x16x32_bf16 v[48:51], v[136:139], v[212:215], v[48:51]
	v_mfma_f32_16x16x32_bf16 v[44:47], v[152:155], v[212:215], v[44:47]
	v_mfma_f32_16x16x32_bf16 v[32:35], v[136:139], v[220:223], v[32:35]
	v_mfma_f32_16x16x32_bf16 v[28:31], v[152:155], v[220:223], v[28:31]
	v_mfma_f32_16x16x32_bf16 v[16:19], v[136:139], v[228:231], v[16:19]
	v_mfma_f32_16x16x32_bf16 v[12:15], v[152:155], v[228:231], v[12:15]
	v_mfma_f32_16x16x32_bf16 v[56:59], v[178:181], v[200:203], v[56:59]
	v_mfma_f32_16x16x32_bf16 v[52:55], v[186:189], v[200:203], v[52:55]
	v_mfma_f32_16x16x32_bf16 v[40:43], v[178:181], v[208:211], v[40:43]
	v_mfma_f32_16x16x32_bf16 v[36:39], v[186:189], v[208:211], v[36:39]
	v_mfma_f32_16x16x32_bf16 v[24:27], v[178:181], v[216:219], v[24:27]
	v_mfma_f32_16x16x32_bf16 v[20:23], v[186:189], v[216:219], v[20:23]
	v_mfma_f32_16x16x32_bf16 v[8:11], v[178:181], v[224:227], v[8:11]
	v_mfma_f32_16x16x32_bf16 v[4:7], v[186:189], v[224:227], v[4:7]
	v_mfma_f32_16x16x32_bf16 v[56:59], v[182:185], v[204:207], v[56:59]
	v_mfma_f32_16x16x32_bf16 v[52:55], v[190:193], v[204:207], v[52:55]
	v_mfma_f32_16x16x32_bf16 v[40:43], v[182:185], v[212:215], v[40:43]
	v_mfma_f32_16x16x32_bf16 v[36:39], v[190:193], v[212:215], v[36:39]
	v_mfma_f32_16x16x32_bf16 v[24:27], v[182:185], v[220:223], v[24:27]
	v_mfma_f32_16x16x32_bf16 v[20:23], v[190:193], v[220:223], v[20:23]
	v_mfma_f32_16x16x32_bf16 v[8:11], v[182:185], v[228:231], v[8:11]
	v_mfma_f32_16x16x32_bf16 v[4:7], v[190:193], v[228:231], v[4:7]
	s_setprio 0
	s_barrier
	s_add_i32 s24, 0, 0x18000
	s_add_i32 s25, 0, 0x1c000
	v_add_u32_e32 v152, s24, v175
	v_add_u32_e32 v190, s25, v175
	ds_read_b128 v[132:135], v152
	ds_read_b128 v[136:139], v152 offset:1024
	ds_read_b128 v[148:151], v152 offset:2048
	ds_read_b128 v[152:155], v152 offset:3072
	ds_read_b128 v[178:181], v190
	ds_read_b128 v[182:185], v190 offset:1024
	ds_read_b128 v[186:189], v190 offset:2048
	ds_read_b128 v[190:193], v190 offset:3072
	s_add_u32 s54, s54, 0x40000
	s_addc_u32 s55, s55, 0
	s_mov_b32 m0, s60
	v_lshl_add_u64 v[238:239], s[54:55], 0, v[142:143]
	ds_read_b128 v[200:203], v177 offset:32768
	ds_read_b128 v[204:207], v177 offset:33792
	ds_read_b128 v[208:211], v177 offset:34816
	ds_read_b128 v[212:215], v177 offset:35840
	ds_read_b128 v[216:219], v177 offset:36864
	ds_read_b128 v[220:223], v177 offset:37888
	ds_read_b128 v[224:227], v177 offset:38912
	ds_read_b128 v[228:231], v177 offset:39936
	global_load_lds_dwordx4 v[238:239], off
	v_lshl_add_u64 v[238:239], s[54:55], 0, v[140:141]
	s_mov_b32 m0, s61
	s_nop 0
	global_load_lds_dwordx4 v[238:239], off
	s_waitcnt vmcnt(8)
	s_waitcnt lgkmcnt(0)
	s_barrier
	s_setprio 1
	v_mfma_f32_16x16x32_bf16 v[128:131], v[132:135], v[200:203], v[128:131]
	v_mfma_f32_16x16x32_bf16 v[124:127], v[148:151], v[200:203], v[124:127]
	v_mfma_f32_16x16x32_bf16 v[112:115], v[132:135], v[208:211], v[112:115]
	v_mfma_f32_16x16x32_bf16 v[108:111], v[148:151], v[208:211], v[108:111]
	v_mfma_f32_16x16x32_bf16 v[96:99], v[132:135], v[216:219], v[96:99]
	v_mfma_f32_16x16x32_bf16 v[92:95], v[148:151], v[216:219], v[92:95]
	v_mfma_f32_16x16x32_bf16 v[80:83], v[132:135], v[224:227], v[80:83]
	v_mfma_f32_16x16x32_bf16 v[76:79], v[148:151], v[224:227], v[76:79]
	v_mfma_f32_16x16x32_bf16 v[128:131], v[136:139], v[204:207], v[128:131]
	v_mfma_f32_16x16x32_bf16 v[124:127], v[152:155], v[204:207], v[124:127]
	v_mfma_f32_16x16x32_bf16 v[112:115], v[136:139], v[212:215], v[112:115]
	v_mfma_f32_16x16x32_bf16 v[108:111], v[152:155], v[212:215], v[108:111]
	v_mfma_f32_16x16x32_bf16 v[96:99], v[136:139], v[220:223], v[96:99]
	v_mfma_f32_16x16x32_bf16 v[92:95], v[152:155], v[220:223], v[92:95]
	v_mfma_f32_16x16x32_bf16 v[80:83], v[136:139], v[228:231], v[80:83]
	v_mfma_f32_16x16x32_bf16 v[76:79], v[152:155], v[228:231], v[76:79]
	v_mfma_f32_16x16x32_bf16 v[120:123], v[178:181], v[200:203], v[120:123]
	v_mfma_f32_16x16x32_bf16 v[116:119], v[186:189], v[200:203], v[116:119]
	v_mfma_f32_16x16x32_bf16 v[104:107], v[178:181], v[208:211], v[104:107]
	v_mfma_f32_16x16x32_bf16 v[100:103], v[186:189], v[208:211], v[100:103]
	v_mfma_f32_16x16x32_bf16 v[88:91], v[178:181], v[216:219], v[88:91]
	v_mfma_f32_16x16x32_bf16 v[84:87], v[186:189], v[216:219], v[84:87]
	v_mfma_f32_16x16x32_bf16 v[72:75], v[178:181], v[224:227], v[72:75]
	v_mfma_f32_16x16x32_bf16 v[68:71], v[186:189], v[224:227], v[68:71]
	v_mfma_f32_16x16x32_bf16 v[120:123], v[182:185], v[204:207], v[120:123]
	v_mfma_f32_16x16x32_bf16 v[116:119], v[190:193], v[204:207], v[116:119]
	v_mfma_f32_16x16x32_bf16 v[104:107], v[182:185], v[212:215], v[104:107]
	v_mfma_f32_16x16x32_bf16 v[100:103], v[190:193], v[212:215], v[100:103]
	v_mfma_f32_16x16x32_bf16 v[88:91], v[182:185], v[220:223], v[88:91]
	v_mfma_f32_16x16x32_bf16 v[84:87], v[190:193], v[220:223], v[84:87]
	v_mfma_f32_16x16x32_bf16 v[72:75], v[182:185], v[228:231], v[72:75]
	v_mfma_f32_16x16x32_bf16 v[68:71], v[190:193], v[228:231], v[68:71]
	s_setprio 0
	s_barrier
	s_add_i32 s24, s24, s22
	v_lshl_add_u64 v[172:173], v[172:173], 0, s[26:27]
	s_mov_b32 m0, s24
	ds_read_b128 v[200:203], v177 offset:49152
	ds_read_b128 v[204:207], v177 offset:50176
	ds_read_b128 v[208:211], v177 offset:51200
	ds_read_b128 v[212:215], v177 offset:52224
	ds_read_b128 v[216:219], v177 offset:53248
	ds_read_b128 v[220:223], v177 offset:54272
	ds_read_b128 v[224:227], v177 offset:55296
	ds_read_b128 v[228:231], v177 offset:56320
	global_load_lds_dwordx4 v[172:173], off
	s_add_i32 m0, s24, 0x2000
	s_add_u32 s14, s14, 0x40080
	v_lshl_add_u64 v[172:173], v[232:233], 0, s[26:27]
	s_addc_u32 s15, s15, 0
	s_add_i32 s24, s25, s22
	global_load_lds_dwordx4 v[172:173], off
	v_lshl_add_u64 v[172:173], s[14:15], 0, v[2:3]
	s_mov_b32 m0, s24
	s_nop 0
	global_load_lds_dwordx4 v[172:173], off
	v_lshl_add_u64 v[172:173], s[14:15], 0, v[0:1]
	s_add_i32 m0, s24, 0x2000
	s_nop 0
	global_load_lds_dwordx4 v[172:173], off
	v_lshl_add_u64 v[172:173], v[234:235], 0, s[26:27]
	s_mov_b32 m0, s64
	s_nop 0
	global_load_lds_dwordx4 v[172:173], off
	v_lshl_add_u64 v[172:173], v[236:237], 0, s[26:27]
	s_mov_b32 m0, s65
	s_nop 0
	global_load_lds_dwordx4 v[172:173], off
	s_waitcnt vmcnt(8)
	s_waitcnt lgkmcnt(0)
	s_barrier
	s_setprio 1
	v_mfma_f32_16x16x32_bf16 v[64:67], v[132:135], v[200:203], v[64:67]
	v_mfma_f32_16x16x32_bf16 v[60:63], v[148:151], v[200:203], v[60:63]
	v_mfma_f32_16x16x32_bf16 v[48:51], v[132:135], v[208:211], v[48:51]
	v_mfma_f32_16x16x32_bf16 v[44:47], v[148:151], v[208:211], v[44:47]
	v_mfma_f32_16x16x32_bf16 v[32:35], v[132:135], v[216:219], v[32:35]
	v_mfma_f32_16x16x32_bf16 v[28:31], v[148:151], v[216:219], v[28:31]
	v_mfma_f32_16x16x32_bf16 v[16:19], v[132:135], v[224:227], v[16:19]
	v_mfma_f32_16x16x32_bf16 v[12:15], v[148:151], v[224:227], v[12:15]
	v_mfma_f32_16x16x32_bf16 v[64:67], v[136:139], v[204:207], v[64:67]
	v_mfma_f32_16x16x32_bf16 v[60:63], v[152:155], v[204:207], v[60:63]
	v_mfma_f32_16x16x32_bf16 v[48:51], v[136:139], v[212:215], v[48:51]
	v_mfma_f32_16x16x32_bf16 v[44:47], v[152:155], v[212:215], v[44:47]
	v_mfma_f32_16x16x32_bf16 v[32:35], v[136:139], v[220:223], v[32:35]
	v_mfma_f32_16x16x32_bf16 v[28:31], v[152:155], v[220:223], v[28:31]
	v_mfma_f32_16x16x32_bf16 v[16:19], v[136:139], v[228:231], v[16:19]
	v_mfma_f32_16x16x32_bf16 v[12:15], v[152:155], v[228:231], v[12:15]
	v_mfma_f32_16x16x32_bf16 v[56:59], v[178:181], v[200:203], v[56:59]
	v_mfma_f32_16x16x32_bf16 v[52:55], v[186:189], v[200:203], v[52:55]
	v_mfma_f32_16x16x32_bf16 v[40:43], v[178:181], v[208:211], v[40:43]
	v_mfma_f32_16x16x32_bf16 v[36:39], v[186:189], v[208:211], v[36:39]
	v_mfma_f32_16x16x32_bf16 v[24:27], v[178:181], v[216:219], v[24:27]
	v_mfma_f32_16x16x32_bf16 v[20:23], v[186:189], v[216:219], v[20:23]
	v_mfma_f32_16x16x32_bf16 v[8:11], v[178:181], v[224:227], v[8:11]
	v_mfma_f32_16x16x32_bf16 v[4:7], v[186:189], v[224:227], v[4:7]
	v_mfma_f32_16x16x32_bf16 v[56:59], v[182:185], v[204:207], v[56:59]
	v_mfma_f32_16x16x32_bf16 v[52:55], v[190:193], v[204:207], v[52:55]
	v_mfma_f32_16x16x32_bf16 v[40:43], v[182:185], v[212:215], v[40:43]
	v_mfma_f32_16x16x32_bf16 v[36:39], v[190:193], v[212:215], v[36:39]
	v_mfma_f32_16x16x32_bf16 v[24:27], v[182:185], v[220:223], v[24:27]
	v_mfma_f32_16x16x32_bf16 v[20:23], v[190:193], v[220:223], v[20:23]
	v_mfma_f32_16x16x32_bf16 v[8:11], v[182:185], v[228:231], v[8:11]
	v_mfma_f32_16x16x32_bf16 v[4:7], v[190:193], v[228:231], v[4:7]
	s_setprio 0
	s_barrier
	s_add_i32 s91, s91, 2
	s_add_u32 s87, s87, 0x100
	s_addc_u32 s89, s89, 0
	s_add_u32 s42, s42, 0x100
	s_addc_u32 s43, s43, 0
	s_cmp_gt_u32 s91, 13
	s_cbranch_scc0 .LBB0_812
	s_and_b64 vcc, exec, s[12:13]
	s_cbranch_vccz .LBB0_815
	s_barrier

.LBB0_960:
	s_add_u32 s14, s42, 0xfffc0080
	s_addc_u32 s15, s43, -1
	s_add_i32 s24, 0, 0x10000
	s_cmp_eq_u32 s63, 12
	s_cselect_b32 s47, s29, s15
	s_cselect_b32 s46, s54, s14
	s_cselect_b32 s15, s13, s61
	s_cselect_b32 s14, s55, s60
	s_add_i32 s25, 0, 0x14000
	v_add_u32_e32 v172, s24, v145
	v_add_u32_e32 v188, s25, v145
	ds_read_b128 v[140:143], v172
	ds_read_b128 v[148:151], v172 offset:1024
	ds_read_b128 v[152:155], v172 offset:2048
	ds_read_b128 v[172:175], v172 offset:3072
	ds_read_b128 v[176:179], v188
	ds_read_b128 v[180:183], v188 offset:1024
	ds_read_b128 v[184:187], v188 offset:2048
	ds_read_b128 v[188:191], v188 offset:3072
	v_lshl_add_u64 v[192:193], s[42:43], 0, v[138:139]
	s_add_i32 m0, s21, 0xc000
	ds_read_b128 v[200:203], v147
	ds_read_b128 v[204:207], v147 offset:1024
	ds_read_b128 v[208:211], v147 offset:2048
	ds_read_b128 v[212:215], v147 offset:3072
	ds_read_b128 v[216:219], v147 offset:4096
	ds_read_b128 v[220:223], v147 offset:5120
	ds_read_b128 v[224:227], v147 offset:6144
	ds_read_b128 v[228:231], v147 offset:7168
	global_load_lds_dwordx4 v[192:193], off
	v_lshl_add_u64 v[192:193], s[42:43], 0, v[136:137]
	s_add_i32 m0, s21, 0xe000
	s_nop 0
	global_load_lds_dwordx4 v[192:193], off
	s_waitcnt vmcnt(8)
	s_waitcnt lgkmcnt(0)
	s_barrier
	s_setprio 1
	v_mfma_f32_16x16x32_bf16 v[124:127], v[140:143], v[200:203], v[124:127]
	v_mfma_f32_16x16x32_bf16 v[116:119], v[152:155], v[200:203], v[116:119]
	v_mfma_f32_16x16x32_bf16 v[108:111], v[140:143], v[208:211], v[108:111]
	v_mfma_f32_16x16x32_bf16 v[104:107], v[152:155], v[208:211], v[104:107]
	v_mfma_f32_16x16x32_bf16 v[92:95], v[140:143], v[216:219], v[92:95]
	v_mfma_f32_16x16x32_bf16 v[88:91], v[152:155], v[216:219], v[88:91]
	v_mfma_f32_16x16x32_bf16 v[76:79], v[140:143], v[224:227], v[76:79]
	v_mfma_f32_16x16x32_bf16 v[72:75], v[152:155], v[224:227], v[72:75]
	v_mfma_f32_16x16x32_bf16 v[124:127], v[148:151], v[204:207], v[124:127]
	v_mfma_f32_16x16x32_bf16 v[116:119], v[172:175], v[204:207], v[116:119]
	v_mfma_f32_16x16x32_bf16 v[108:111], v[148:151], v[212:215], v[108:111]
	v_mfma_f32_16x16x32_bf16 v[104:107], v[172:175], v[212:215], v[104:107]
	v_mfma_f32_16x16x32_bf16 v[92:95], v[148:151], v[220:223], v[92:95]
	v_mfma_f32_16x16x32_bf16 v[88:91], v[172:175], v[220:223], v[88:91]
	v_mfma_f32_16x16x32_bf16 v[76:79], v[148:151], v[228:231], v[76:79]
	v_mfma_f32_16x16x32_bf16 v[72:75], v[172:175], v[228:231], v[72:75]
	v_mfma_f32_16x16x32_bf16 v[128:131], v[176:179], v[200:203], v[128:131]
	v_mfma_f32_16x16x32_bf16 v[120:123], v[184:187], v[200:203], v[120:123]
	v_mfma_f32_16x16x32_bf16 v[112:115], v[176:179], v[208:211], v[112:115]
	v_mfma_f32_16x16x32_bf16 v[100:103], v[184:187], v[208:211], v[100:103]
	v_mfma_f32_16x16x32_bf16 v[96:99], v[176:179], v[216:219], v[96:99]
	v_mfma_f32_16x16x32_bf16 v[84:87], v[184:187], v[216:219], v[84:87]
	v_mfma_f32_16x16x32_bf16 v[80:83], v[176:179], v[224:227], v[80:83]
	v_mfma_f32_16x16x32_bf16 v[68:71], v[184:187], v[224:227], v[68:71]
	v_mfma_f32_16x16x32_bf16 v[128:131], v[180:183], v[204:207], v[128:131]
	v_mfma_f32_16x16x32_bf16 v[120:123], v[188:191], v[204:207], v[120:123]
	v_mfma_f32_16x16x32_bf16 v[112:115], v[180:183], v[212:215], v[112:115]
	v_mfma_f32_16x16x32_bf16 v[100:103], v[188:191], v[212:215], v[100:103]
	v_mfma_f32_16x16x32_bf16 v[96:99], v[180:183], v[220:223], v[96:99]
	v_mfma_f32_16x16x32_bf16 v[84:87], v[188:191], v[220:223], v[84:87]
	v_mfma_f32_16x16x32_bf16 v[80:83], v[180:183], v[228:231], v[80:83]
	v_mfma_f32_16x16x32_bf16 v[68:71], v[188:191], v[228:231], v[68:71]
	s_setprio 0
	s_barrier
	s_add_i32 s24, s24, s20
	v_lshl_add_u64 v[192:193], s[14:15], 0, v[2:3]
	s_mov_b32 m0, s24
	ds_read_b128 v[200:203], v147 offset:16384
	ds_read_b128 v[204:207], v147 offset:17408
	ds_read_b128 v[208:211], v147 offset:18432
	ds_read_b128 v[212:215], v147 offset:19456
	ds_read_b128 v[216:219], v147 offset:20480
	ds_read_b128 v[220:223], v147 offset:21504
	ds_read_b128 v[224:227], v147 offset:22528
	ds_read_b128 v[228:231], v147 offset:23552
	global_load_lds_dwordx4 v[192:193], off
	s_add_i32 m0, s24, 0x2000
	s_add_u32 s64, s14, 0x40000
	v_lshl_add_u64 v[232:233], s[14:15], 0, v[0:1]
	s_addc_u32 s65, s15, 0
	s_add_i32 s24, s25, s20
	global_load_lds_dwordx4 v[232:233], off
	v_lshl_add_u64 v[234:235], s[64:65], 0, v[2:3]
	s_mov_b32 m0, s24
	v_lshl_add_u64 v[236:237], s[46:47], 0, v[132:133]
	global_load_lds_dwordx4 v[234:235], off
	v_lshl_add_u64 v[234:235], s[64:65], 0, v[0:1]
	s_add_i32 m0, s24, 0x2000
	s_nop 0
	global_load_lds_dwordx4 v[234:235], off
	v_lshl_add_u64 v[234:235], s[46:47], 0, v[134:135]
	s_mov_b32 m0, s21
	s_nop 0
	global_load_lds_dwordx4 v[234:235], off
	s_mov_b32 m0, s22
	s_nop 0
	global_load_lds_dwordx4 v[236:237], off
	s_waitcnt vmcnt(8)
	s_waitcnt lgkmcnt(0)
	s_barrier
	s_setprio 1
	v_mfma_f32_16x16x32_bf16 v[60:63], v[140:143], v[200:203], v[60:63]
	v_mfma_f32_16x16x32_bf16 v[56:59], v[152:155], v[200:203], v[56:59]
	v_mfma_f32_16x16x32_bf16 v[44:47], v[140:143], v[208:211], v[44:47]
	v_mfma_f32_16x16x32_bf16 v[40:43], v[152:155], v[208:211], v[40:43]
	v_mfma_f32_16x16x32_bf16 v[28:31], v[140:143], v[216:219], v[28:31]
	v_mfma_f32_16x16x32_bf16 v[24:27], v[152:155], v[216:219], v[24:27]
	v_mfma_f32_16x16x32_bf16 v[12:15], v[140:143], v[224:227], v[12:15]
	v_mfma_f32_16x16x32_bf16 v[4:7], v[152:155], v[224:227], v[4:7]
	v_mfma_f32_16x16x32_bf16 v[60:63], v[148:151], v[204:207], v[60:63]
	v_mfma_f32_16x16x32_bf16 v[56:59], v[172:175], v[204:207], v[56:59]
	v_mfma_f32_16x16x32_bf16 v[44:47], v[148:151], v[212:215], v[44:47]
	v_mfma_f32_16x16x32_bf16 v[40:43], v[172:175], v[212:215], v[40:43]
	v_mfma_f32_16x16x32_bf16 v[28:31], v[148:151], v[220:223], v[28:31]
	v_mfma_f32_16x16x32_bf16 v[24:27], v[172:175], v[220:223], v[24:27]
	v_mfma_f32_16x16x32_bf16 v[12:15], v[148:151], v[228:231], v[12:15]
	v_mfma_f32_16x16x32_bf16 v[4:7], v[172:175], v[228:231], v[4:7]
	v_mfma_f32_16x16x32_bf16 v[64:67], v[176:179], v[200:203], v[64:67]
	v_mfma_f32_16x16x32_bf16 v[52:55], v[184:187], v[200:203], v[52:55]
	v_mfma_f32_16x16x32_bf16 v[48:51], v[176:179], v[208:211], v[48:51]
	v_mfma_f32_16x16x32_bf16 v[36:39], v[184:187], v[208:211], v[36:39]
	v_mfma_f32_16x16x32_bf16 v[32:35], v[176:179], v[216:219], v[32:35]
	v_mfma_f32_16x16x32_bf16 v[20:23], v[184:187], v[216:219], v[20:23]
	v_mfma_f32_16x16x32_bf16 v[16:19], v[176:179], v[224:227], v[16:19]
	v_mfma_f32_16x16x32_bf16 v[8:11], v[184:187], v[224:227], v[8:11]
	v_mfma_f32_16x16x32_bf16 v[64:67], v[180:183], v[204:207], v[64:67]
	v_mfma_f32_16x16x32_bf16 v[52:55], v[188:191], v[204:207], v[52:55]
	v_mfma_f32_16x16x32_bf16 v[48:51], v[180:183], v[212:215], v[48:51]
	v_mfma_f32_16x16x32_bf16 v[36:39], v[188:191], v[212:215], v[36:39]
	v_mfma_f32_16x16x32_bf16 v[32:35], v[180:183], v[220:223], v[32:35]
	v_mfma_f32_16x16x32_bf16 v[20:23], v[188:191], v[220:223], v[20:23]
	v_mfma_f32_16x16x32_bf16 v[16:19], v[180:183], v[228:231], v[16:19]
	v_mfma_f32_16x16x32_bf16 v[8:11], v[188:191], v[228:231], v[8:11]
	s_setprio 0
	s_barrier
	s_add_i32 s24, 0, 0x18000
	s_add_i32 s25, 0, 0x1c000
	v_add_u32_e32 v172, s24, v145
	v_add_u32_e32 v188, s25, v145
	ds_read_b128 v[140:143], v172
	ds_read_b128 v[148:151], v172 offset:1024
	ds_read_b128 v[152:155], v172 offset:2048
	ds_read_b128 v[172:175], v172 offset:3072
	ds_read_b128 v[176:179], v188
	ds_read_b128 v[180:183], v188 offset:1024
	ds_read_b128 v[184:187], v188 offset:2048
	ds_read_b128 v[188:191], v188 offset:3072
	s_add_u32 s46, s46, 0x40000
	s_addc_u32 s47, s47, 0
	s_mov_b32 m0, s23
	v_lshl_add_u64 v[238:239], s[46:47], 0, v[134:135]
	ds_read_b128 v[200:203], v147 offset:32768
	ds_read_b128 v[204:207], v147 offset:33792
	ds_read_b128 v[208:211], v147 offset:34816
	ds_read_b128 v[212:215], v147 offset:35840
	ds_read_b128 v[216:219], v147 offset:36864
	ds_read_b128 v[220:223], v147 offset:37888
	ds_read_b128 v[224:227], v147 offset:38912
	ds_read_b128 v[228:231], v147 offset:39936
	global_load_lds_dwordx4 v[238:239], off
	v_lshl_add_u64 v[238:239], s[46:47], 0, v[132:133]
	s_mov_b32 m0, s45
	s_nop 0
	global_load_lds_dwordx4 v[238:239], off
	s_waitcnt vmcnt(8)
	s_waitcnt lgkmcnt(0)
	s_barrier
	s_setprio 1
	v_mfma_f32_16x16x32_bf16 v[124:127], v[140:143], v[200:203], v[124:127]
	v_mfma_f32_16x16x32_bf16 v[116:119], v[152:155], v[200:203], v[116:119]
	v_mfma_f32_16x16x32_bf16 v[108:111], v[140:143], v[208:211], v[108:111]
	v_mfma_f32_16x16x32_bf16 v[104:107], v[152:155], v[208:211], v[104:107]
	v_mfma_f32_16x16x32_bf16 v[92:95], v[140:143], v[216:219], v[92:95]
	v_mfma_f32_16x16x32_bf16 v[88:91], v[152:155], v[216:219], v[88:91]
	v_mfma_f32_16x16x32_bf16 v[76:79], v[140:143], v[224:227], v[76:79]
	v_mfma_f32_16x16x32_bf16 v[72:75], v[152:155], v[224:227], v[72:75]
	v_mfma_f32_16x16x32_bf16 v[124:127], v[148:151], v[204:207], v[124:127]
	v_mfma_f32_16x16x32_bf16 v[116:119], v[172:175], v[204:207], v[116:119]
	v_mfma_f32_16x16x32_bf16 v[108:111], v[148:151], v[212:215], v[108:111]
	v_mfma_f32_16x16x32_bf16 v[104:107], v[172:175], v[212:215], v[104:107]
	v_mfma_f32_16x16x32_bf16 v[92:95], v[148:151], v[220:223], v[92:95]
	v_mfma_f32_16x16x32_bf16 v[88:91], v[172:175], v[220:223], v[88:91]
	v_mfma_f32_16x16x32_bf16 v[76:79], v[148:151], v[228:231], v[76:79]
	v_mfma_f32_16x16x32_bf16 v[72:75], v[172:175], v[228:231], v[72:75]
	v_mfma_f32_16x16x32_bf16 v[128:131], v[176:179], v[200:203], v[128:131]
	v_mfma_f32_16x16x32_bf16 v[120:123], v[184:187], v[200:203], v[120:123]
	v_mfma_f32_16x16x32_bf16 v[112:115], v[176:179], v[208:211], v[112:115]
	v_mfma_f32_16x16x32_bf16 v[100:103], v[184:187], v[208:211], v[100:103]
	v_mfma_f32_16x16x32_bf16 v[96:99], v[176:179], v[216:219], v[96:99]
	v_mfma_f32_16x16x32_bf16 v[84:87], v[184:187], v[216:219], v[84:87]
	v_mfma_f32_16x16x32_bf16 v[80:83], v[176:179], v[224:227], v[80:83]
	v_mfma_f32_16x16x32_bf16 v[68:71], v[184:187], v[224:227], v[68:71]
	v_mfma_f32_16x16x32_bf16 v[128:131], v[180:183], v[204:207], v[128:131]
	v_mfma_f32_16x16x32_bf16 v[120:123], v[188:191], v[204:207], v[120:123]
	v_mfma_f32_16x16x32_bf16 v[112:115], v[180:183], v[212:215], v[112:115]
	v_mfma_f32_16x16x32_bf16 v[100:103], v[188:191], v[212:215], v[100:103]
	v_mfma_f32_16x16x32_bf16 v[96:99], v[180:183], v[220:223], v[96:99]
	v_mfma_f32_16x16x32_bf16 v[84:87], v[188:191], v[220:223], v[84:87]
	v_mfma_f32_16x16x32_bf16 v[80:83], v[180:183], v[228:231], v[80:83]
	v_mfma_f32_16x16x32_bf16 v[68:71], v[188:191], v[228:231], v[68:71]
	s_setprio 0
	s_barrier
	s_add_i32 s24, s24, s20
	v_lshl_add_u64 v[192:193], v[192:193], 0, s[26:27]
	s_mov_b32 m0, s24
	ds_read_b128 v[200:203], v147 offset:49152
	ds_read_b128 v[204:207], v147 offset:50176
	ds_read_b128 v[208:211], v147 offset:51200
	ds_read_b128 v[212:215], v147 offset:52224
	ds_read_b128 v[216:219], v147 offset:53248
	ds_read_b128 v[220:223], v147 offset:54272
	ds_read_b128 v[224:227], v147 offset:55296
	ds_read_b128 v[228:231], v147 offset:56320
	global_load_lds_dwordx4 v[192:193], off
	s_add_i32 m0, s24, 0x2000
	s_add_u32 s14, s14, 0x40080
	v_lshl_add_u64 v[192:193], v[232:233], 0, s[26:27]
	s_addc_u32 s15, s15, 0
	s_add_i32 s24, s25, s20
	global_load_lds_dwordx4 v[192:193], off
	v_lshl_add_u64 v[192:193], s[14:15], 0, v[2:3]
	s_mov_b32 m0, s24
	s_nop 0
	global_load_lds_dwordx4 v[192:193], off
	v_lshl_add_u64 v[192:193], s[14:15], 0, v[0:1]
	s_add_i32 m0, s24, 0x2000
	s_nop 0
	global_load_lds_dwordx4 v[192:193], off
	v_lshl_add_u64 v[192:193], v[234:235], 0, s[26:27]
	s_mov_b32 m0, s36
	s_nop 0
	global_load_lds_dwordx4 v[192:193], off
	v_lshl_add_u64 v[192:193], v[236:237], 0, s[26:27]
	s_mov_b32 m0, s48
	s_nop 0
	global_load_lds_dwordx4 v[192:193], off
	s_waitcnt vmcnt(8)
	s_waitcnt lgkmcnt(0)
	s_barrier
	s_setprio 1
	v_mfma_f32_16x16x32_bf16 v[60:63], v[140:143], v[200:203], v[60:63]
	v_mfma_f32_16x16x32_bf16 v[56:59], v[152:155], v[200:203], v[56:59]
	v_mfma_f32_16x16x32_bf16 v[44:47], v[140:143], v[208:211], v[44:47]
	v_mfma_f32_16x16x32_bf16 v[40:43], v[152:155], v[208:211], v[40:43]
	v_mfma_f32_16x16x32_bf16 v[28:31], v[140:143], v[216:219], v[28:31]
	v_mfma_f32_16x16x32_bf16 v[24:27], v[152:155], v[216:219], v[24:27]
	v_mfma_f32_16x16x32_bf16 v[12:15], v[140:143], v[224:227], v[12:15]
	v_mfma_f32_16x16x32_bf16 v[4:7], v[152:155], v[224:227], v[4:7]
	v_mfma_f32_16x16x32_bf16 v[60:63], v[148:151], v[204:207], v[60:63]
	v_mfma_f32_16x16x32_bf16 v[56:59], v[172:175], v[204:207], v[56:59]
	v_mfma_f32_16x16x32_bf16 v[44:47], v[148:151], v[212:215], v[44:47]
	v_mfma_f32_16x16x32_bf16 v[40:43], v[172:175], v[212:215], v[40:43]
	v_mfma_f32_16x16x32_bf16 v[28:31], v[148:151], v[220:223], v[28:31]
	v_mfma_f32_16x16x32_bf16 v[24:27], v[172:175], v[220:223], v[24:27]
	v_mfma_f32_16x16x32_bf16 v[12:15], v[148:151], v[228:231], v[12:15]
	v_mfma_f32_16x16x32_bf16 v[4:7], v[172:175], v[228:231], v[4:7]
	v_mfma_f32_16x16x32_bf16 v[64:67], v[176:179], v[200:203], v[64:67]
	v_mfma_f32_16x16x32_bf16 v[52:55], v[184:187], v[200:203], v[52:55]
	v_mfma_f32_16x16x32_bf16 v[48:51], v[176:179], v[208:211], v[48:51]
	v_mfma_f32_16x16x32_bf16 v[36:39], v[184:187], v[208:211], v[36:39]
	v_mfma_f32_16x16x32_bf16 v[32:35], v[176:179], v[216:219], v[32:35]
	v_mfma_f32_16x16x32_bf16 v[20:23], v[184:187], v[216:219], v[20:23]
	v_mfma_f32_16x16x32_bf16 v[16:19], v[176:179], v[224:227], v[16:19]
	v_mfma_f32_16x16x32_bf16 v[8:11], v[184:187], v[224:227], v[8:11]
	v_mfma_f32_16x16x32_bf16 v[64:67], v[180:183], v[204:207], v[64:67]
	v_mfma_f32_16x16x32_bf16 v[52:55], v[188:191], v[204:207], v[52:55]
	v_mfma_f32_16x16x32_bf16 v[48:51], v[180:183], v[212:215], v[48:51]
	v_mfma_f32_16x16x32_bf16 v[36:39], v[188:191], v[212:215], v[36:39]
	v_mfma_f32_16x16x32_bf16 v[32:35], v[180:183], v[220:223], v[32:35]
	v_mfma_f32_16x16x32_bf16 v[20:23], v[188:191], v[220:223], v[20:23]
	v_mfma_f32_16x16x32_bf16 v[16:19], v[180:183], v[228:231], v[16:19]
	v_mfma_f32_16x16x32_bf16 v[8:11], v[188:191], v[228:231], v[8:11]
	s_setprio 0
	s_barrier
	s_add_i32 s63, s63, 2
	s_add_u32 s60, s60, 0x100
	s_addc_u32 s61, s61, 0
	s_add_u32 s42, s42, 0x100
	s_addc_u32 s43, s43, 0
	s_cmp_gt_u32 s63, 13
	s_cbranch_scc0 .LBB0_960
	s_and_b64 vcc, exec, s[10:11]
	s_cbranch_vccz .LBB0_963
	s_barrier

.LBB0_1044:
	s_add_u32 s14, s38, 0x100
	s_addc_u32 s15, s39, 0
	s_add_i32 s24, 0, 0x10000
	s_cmp_eq_u32 s61, 40
	s_cselect_b32 s45, s13, s15
	s_cselect_b32 s44, s12, s14
	v_add_u32_e32 v144, s24, v147
	s_cselect_b32 s43, s29, s60
	s_cselect_b32 s42, s28, s55
	s_add_i32 s25, 0, 0x14000
	ds_read_b128 v[140:143], v144
	ds_read_b128 v[150:153], v144 offset:1024
	ds_read_b128 v[172:175], v144 offset:2048
	ds_read_b128 v[176:179], v144 offset:3072
	v_add_u32_e32 v144, s25, v147
	ds_read_b128 v[180:183], v144
	ds_read_b128 v[184:187], v144 offset:1024
	ds_read_b128 v[188:191], v144 offset:2048
	ds_read_b128 v[200:203], v144 offset:3072
	v_lshl_add_u64 v[144:145], s[38:39], 0, v[138:139]
	s_add_i32 m0, s21, 0xc000
	ds_read_b128 v[204:207], v149
	ds_read_b128 v[208:211], v149 offset:1024
	ds_read_b128 v[212:215], v149 offset:2048
	ds_read_b128 v[216:219], v149 offset:3072
	ds_read_b128 v[220:223], v149 offset:4096
	ds_read_b128 v[224:227], v149 offset:5120
	ds_read_b128 v[228:231], v149 offset:6144
	ds_read_b128 v[232:235], v149 offset:7168
	global_load_lds_dwordx4 v[144:145], off
	v_lshl_add_u64 v[144:145], s[38:39], 0, v[136:137]
	s_add_i32 m0, s21, 0xe000
	s_nop 0
	global_load_lds_dwordx4 v[144:145], off
	s_waitcnt vmcnt(8)
	s_waitcnt lgkmcnt(0)
	s_barrier
	s_setprio 1
	v_mfma_f32_16x16x32_bf16 v[128:131], v[140:143], v[204:207], v[128:131]
	v_mfma_f32_16x16x32_bf16 v[124:127], v[172:175], v[204:207], v[124:127]
	v_mfma_f32_16x16x32_bf16 v[112:115], v[140:143], v[212:215], v[112:115]
	v_mfma_f32_16x16x32_bf16 v[108:111], v[172:175], v[212:215], v[108:111]
	v_mfma_f32_16x16x32_bf16 v[96:99], v[140:143], v[220:223], v[96:99]
	v_mfma_f32_16x16x32_bf16 v[92:95], v[172:175], v[220:223], v[92:95]
	v_mfma_f32_16x16x32_bf16 v[80:83], v[140:143], v[228:231], v[80:83]
	v_mfma_f32_16x16x32_bf16 v[76:79], v[172:175], v[228:231], v[76:79]
	v_mfma_f32_16x16x32_bf16 v[128:131], v[150:153], v[208:211], v[128:131]
	v_mfma_f32_16x16x32_bf16 v[124:127], v[176:179], v[208:211], v[124:127]
	v_mfma_f32_16x16x32_bf16 v[112:115], v[150:153], v[216:219], v[112:115]
	v_mfma_f32_16x16x32_bf16 v[108:111], v[176:179], v[216:219], v[108:111]
	v_mfma_f32_16x16x32_bf16 v[96:99], v[150:153], v[224:227], v[96:99]
	v_mfma_f32_16x16x32_bf16 v[92:95], v[176:179], v[224:227], v[92:95]
	v_mfma_f32_16x16x32_bf16 v[80:83], v[150:153], v[232:235], v[80:83]
	v_mfma_f32_16x16x32_bf16 v[76:79], v[176:179], v[232:235], v[76:79]
	v_mfma_f32_16x16x32_bf16 v[120:123], v[180:183], v[204:207], v[120:123]
	v_mfma_f32_16x16x32_bf16 v[116:119], v[188:191], v[204:207], v[116:119]
	v_mfma_f32_16x16x32_bf16 v[104:107], v[180:183], v[212:215], v[104:107]
	v_mfma_f32_16x16x32_bf16 v[100:103], v[188:191], v[212:215], v[100:103]
	v_mfma_f32_16x16x32_bf16 v[88:91], v[180:183], v[220:223], v[88:91]
	v_mfma_f32_16x16x32_bf16 v[84:87], v[188:191], v[220:223], v[84:87]
	v_mfma_f32_16x16x32_bf16 v[72:75], v[180:183], v[228:231], v[72:75]
	v_mfma_f32_16x16x32_bf16 v[68:71], v[188:191], v[228:231], v[68:71]
	v_mfma_f32_16x16x32_bf16 v[120:123], v[184:187], v[208:211], v[120:123]
	v_mfma_f32_16x16x32_bf16 v[116:119], v[200:203], v[208:211], v[116:119]
	v_mfma_f32_16x16x32_bf16 v[104:107], v[184:187], v[216:219], v[104:107]
	v_mfma_f32_16x16x32_bf16 v[100:103], v[200:203], v[216:219], v[100:103]
	v_mfma_f32_16x16x32_bf16 v[88:91], v[184:187], v[224:227], v[88:91]
	v_mfma_f32_16x16x32_bf16 v[84:87], v[200:203], v[224:227], v[84:87]
	v_mfma_f32_16x16x32_bf16 v[72:75], v[184:187], v[232:235], v[72:75]
	v_mfma_f32_16x16x32_bf16 v[68:71], v[200:203], v[232:235], v[68:71]
	s_setprio 0
	s_barrier
	s_add_i32 s24, s24, s20
	v_lshl_add_u64 v[144:145], s[42:43], 0, v[2:3]
	s_mov_b32 m0, s24
	ds_read_b128 v[204:207], v149 offset:16384
	ds_read_b128 v[208:211], v149 offset:17408
	ds_read_b128 v[212:215], v149 offset:18432
	ds_read_b128 v[216:219], v149 offset:19456
	ds_read_b128 v[220:223], v149 offset:20480
	ds_read_b128 v[224:227], v149 offset:21504
	ds_read_b128 v[228:231], v149 offset:22528
	ds_read_b128 v[232:235], v149 offset:23552
	global_load_lds_dwordx4 v[144:145], off
	s_add_i32 m0, s24, 0x2000
	s_add_u32 s38, s42, 0xb0000
	v_lshl_add_u64 v[154:155], s[42:43], 0, v[134:135]
	s_addc_u32 s39, s43, 0
	s_add_i32 s24, s25, s20
	global_load_lds_dwordx4 v[154:155], off
	v_lshl_add_u64 v[192:193], s[38:39], 0, v[2:3]
	s_mov_b32 m0, s24
	v_lshl_add_u64 v[236:237], s[44:45], 0, v[132:133]
	global_load_lds_dwordx4 v[192:193], off
	v_lshl_add_u64 v[192:193], s[38:39], 0, v[134:135]
	s_add_i32 m0, s24, 0x2000
	s_nop 0
	global_load_lds_dwordx4 v[192:193], off
	v_lshl_add_u64 v[192:193], s[44:45], 0, v[0:1]
	s_mov_b32 m0, s21
	s_nop 0
	global_load_lds_dwordx4 v[192:193], off
	s_mov_b32 m0, s22
	s_nop 0
	global_load_lds_dwordx4 v[236:237], off
	s_waitcnt vmcnt(8)
	s_waitcnt lgkmcnt(0)
	s_barrier
	s_setprio 1
	v_mfma_f32_16x16x32_bf16 v[64:67], v[140:143], v[204:207], v[64:67]
	v_mfma_f32_16x16x32_bf16 v[60:63], v[172:175], v[204:207], v[60:63]
	v_mfma_f32_16x16x32_bf16 v[48:51], v[140:143], v[212:215], v[48:51]
	v_mfma_f32_16x16x32_bf16 v[44:47], v[172:175], v[212:215], v[44:47]
	v_mfma_f32_16x16x32_bf16 v[32:35], v[140:143], v[220:223], v[32:35]
	v_mfma_f32_16x16x32_bf16 v[28:31], v[172:175], v[220:223], v[28:31]
	v_mfma_f32_16x16x32_bf16 v[16:19], v[140:143], v[228:231], v[16:19]
	v_mfma_f32_16x16x32_bf16 v[12:15], v[172:175], v[228:231], v[12:15]
	v_mfma_f32_16x16x32_bf16 v[64:67], v[150:153], v[208:211], v[64:67]
	v_mfma_f32_16x16x32_bf16 v[60:63], v[176:179], v[208:211], v[60:63]
	v_mfma_f32_16x16x32_bf16 v[48:51], v[150:153], v[216:219], v[48:51]
	v_mfma_f32_16x16x32_bf16 v[44:47], v[176:179], v[216:219], v[44:47]
	v_mfma_f32_16x16x32_bf16 v[32:35], v[150:153], v[224:227], v[32:35]
	v_mfma_f32_16x16x32_bf16 v[28:31], v[176:179], v[224:227], v[28:31]
	v_mfma_f32_16x16x32_bf16 v[16:19], v[150:153], v[232:235], v[16:19]
	v_mfma_f32_16x16x32_bf16 v[12:15], v[176:179], v[232:235], v[12:15]
	v_mfma_f32_16x16x32_bf16 v[56:59], v[180:183], v[204:207], v[56:59]
	v_mfma_f32_16x16x32_bf16 v[52:55], v[188:191], v[204:207], v[52:55]
	v_mfma_f32_16x16x32_bf16 v[40:43], v[180:183], v[212:215], v[40:43]
	v_mfma_f32_16x16x32_bf16 v[36:39], v[188:191], v[212:215], v[36:39]
	v_mfma_f32_16x16x32_bf16 v[24:27], v[180:183], v[220:223], v[24:27]
	v_mfma_f32_16x16x32_bf16 v[20:23], v[188:191], v[220:223], v[20:23]
	v_mfma_f32_16x16x32_bf16 v[8:11], v[180:183], v[228:231], v[8:11]
	v_mfma_f32_16x16x32_bf16 v[4:7], v[188:191], v[228:231], v[4:7]
	v_mfma_f32_16x16x32_bf16 v[56:59], v[184:187], v[208:211], v[56:59]
	v_mfma_f32_16x16x32_bf16 v[52:55], v[200:203], v[208:211], v[52:55]
	v_mfma_f32_16x16x32_bf16 v[40:43], v[184:187], v[216:219], v[40:43]
	v_mfma_f32_16x16x32_bf16 v[36:39], v[200:203], v[216:219], v[36:39]
	v_mfma_f32_16x16x32_bf16 v[24:27], v[184:187], v[224:227], v[24:27]
	v_mfma_f32_16x16x32_bf16 v[20:23], v[200:203], v[224:227], v[20:23]
	v_mfma_f32_16x16x32_bf16 v[8:11], v[184:187], v[232:235], v[8:11]
	v_mfma_f32_16x16x32_bf16 v[4:7], v[200:203], v[232:235], v[4:7]
	s_setprio 0
	s_barrier
	s_add_i32 s24, 0, 0x18000
	s_add_i32 s25, 0, 0x1c000
	v_add_u32_e32 v176, s24, v147
	v_add_u32_e32 v199, s25, v147
	ds_read_b128 v[140:143], v176
	ds_read_b128 v[150:153], v176 offset:1024
	ds_read_b128 v[172:175], v176 offset:2048
	ds_read_b128 v[176:179], v176 offset:3072
	ds_read_b128 v[180:183], v199
	ds_read_b128 v[184:187], v199 offset:1024
	ds_read_b128 v[188:191], v199 offset:2048
	ds_read_b128 v[200:203], v199 offset:3072
	s_add_u32 s38, s44, 0xb0000
	s_addc_u32 s39, s45, 0
	s_mov_b32 m0, s23
	v_lshl_add_u64 v[238:239], s[38:39], 0, v[0:1]
	ds_read_b128 v[204:207], v149 offset:32768
	ds_read_b128 v[208:211], v149 offset:33792
	ds_read_b128 v[212:215], v149 offset:34816
	ds_read_b128 v[216:219], v149 offset:35840
	ds_read_b128 v[220:223], v149 offset:36864
	ds_read_b128 v[224:227], v149 offset:37888
	ds_read_b128 v[228:231], v149 offset:38912
	ds_read_b128 v[232:235], v149 offset:39936
	global_load_lds_dwordx4 v[238:239], off
	v_lshl_add_u64 v[238:239], s[38:39], 0, v[132:133]
	s_mov_b32 m0, s36
	s_nop 0
	global_load_lds_dwordx4 v[238:239], off
	s_waitcnt vmcnt(8)
	s_waitcnt lgkmcnt(0)
	s_barrier
	s_setprio 1
	v_mfma_f32_16x16x32_bf16 v[128:131], v[140:143], v[204:207], v[128:131]
	v_mfma_f32_16x16x32_bf16 v[124:127], v[172:175], v[204:207], v[124:127]
	v_mfma_f32_16x16x32_bf16 v[112:115], v[140:143], v[212:215], v[112:115]
	v_mfma_f32_16x16x32_bf16 v[108:111], v[172:175], v[212:215], v[108:111]
	v_mfma_f32_16x16x32_bf16 v[96:99], v[140:143], v[220:223], v[96:99]
	v_mfma_f32_16x16x32_bf16 v[92:95], v[172:175], v[220:223], v[92:95]
	v_mfma_f32_16x16x32_bf16 v[80:83], v[140:143], v[228:231], v[80:83]
	v_mfma_f32_16x16x32_bf16 v[76:79], v[172:175], v[228:231], v[76:79]
	v_mfma_f32_16x16x32_bf16 v[128:131], v[150:153], v[208:211], v[128:131]
	v_mfma_f32_16x16x32_bf16 v[124:127], v[176:179], v[208:211], v[124:127]
	v_mfma_f32_16x16x32_bf16 v[112:115], v[150:153], v[216:219], v[112:115]
	v_mfma_f32_16x16x32_bf16 v[108:111], v[176:179], v[216:219], v[108:111]
	v_mfma_f32_16x16x32_bf16 v[96:99], v[150:153], v[224:227], v[96:99]
	v_mfma_f32_16x16x32_bf16 v[92:95], v[176:179], v[224:227], v[92:95]
	v_mfma_f32_16x16x32_bf16 v[80:83], v[150:153], v[232:235], v[80:83]
	v_mfma_f32_16x16x32_bf16 v[76:79], v[176:179], v[232:235], v[76:79]
	v_mfma_f32_16x16x32_bf16 v[120:123], v[180:183], v[204:207], v[120:123]
	v_mfma_f32_16x16x32_bf16 v[116:119], v[188:191], v[204:207], v[116:119]
	v_mfma_f32_16x16x32_bf16 v[104:107], v[180:183], v[212:215], v[104:107]
	v_mfma_f32_16x16x32_bf16 v[100:103], v[188:191], v[212:215], v[100:103]
	v_mfma_f32_16x16x32_bf16 v[88:91], v[180:183], v[220:223], v[88:91]
	v_mfma_f32_16x16x32_bf16 v[84:87], v[188:191], v[220:223], v[84:87]
	v_mfma_f32_16x16x32_bf16 v[72:75], v[180:183], v[228:231], v[72:75]
	v_mfma_f32_16x16x32_bf16 v[68:71], v[188:191], v[228:231], v[68:71]
	v_mfma_f32_16x16x32_bf16 v[120:123], v[184:187], v[208:211], v[120:123]
	v_mfma_f32_16x16x32_bf16 v[116:119], v[200:203], v[208:211], v[116:119]
	v_mfma_f32_16x16x32_bf16 v[104:107], v[184:187], v[216:219], v[104:107]
	v_mfma_f32_16x16x32_bf16 v[100:103], v[200:203], v[216:219], v[100:103]
	v_mfma_f32_16x16x32_bf16 v[88:91], v[184:187], v[224:227], v[88:91]
	v_mfma_f32_16x16x32_bf16 v[84:87], v[200:203], v[224:227], v[84:87]
	v_mfma_f32_16x16x32_bf16 v[72:75], v[184:187], v[232:235], v[72:75]
	v_mfma_f32_16x16x32_bf16 v[68:71], v[200:203], v[232:235], v[68:71]
	s_setprio 0
	s_barrier
	s_add_i32 s24, s24, s20
	v_lshl_add_u64 v[144:145], v[144:145], 0, s[26:27]
	s_mov_b32 m0, s24
	ds_read_b128 v[204:207], v149 offset:49152
	ds_read_b128 v[208:211], v149 offset:50176
	ds_read_b128 v[212:215], v149 offset:51200
	ds_read_b128 v[216:219], v149 offset:52224
	ds_read_b128 v[220:223], v149 offset:53248
	ds_read_b128 v[224:227], v149 offset:54272
	ds_read_b128 v[228:231], v149 offset:55296
	ds_read_b128 v[232:235], v149 offset:56320
	global_load_lds_dwordx4 v[144:145], off
	s_add_i32 m0, s24, 0x2000
	s_add_u32 s38, s42, 0xb0080
	v_lshl_add_u64 v[144:145], v[154:155], 0, s[26:27]
	s_addc_u32 s39, s43, 0
	s_add_i32 s24, s25, s20
	global_load_lds_dwordx4 v[144:145], off
	v_lshl_add_u64 v[144:145], s[38:39], 0, v[2:3]
	s_mov_b32 m0, s24
	s_nop 0
	global_load_lds_dwordx4 v[144:145], off
	v_lshl_add_u64 v[144:145], s[38:39], 0, v[134:135]
	s_add_i32 m0, s24, 0x2000
	s_nop 0
	global_load_lds_dwordx4 v[144:145], off
	v_lshl_add_u64 v[144:145], v[192:193], 0, s[26:27]
	s_mov_b32 m0, s46
	s_nop 0
	global_load_lds_dwordx4 v[144:145], off
	v_lshl_add_u64 v[144:145], v[236:237], 0, s[26:27]
	s_mov_b32 m0, s47
	s_nop 0
	global_load_lds_dwordx4 v[144:145], off
	s_waitcnt vmcnt(8)
	s_waitcnt lgkmcnt(0)
	s_barrier
	s_setprio 1
	v_mfma_f32_16x16x32_bf16 v[64:67], v[140:143], v[204:207], v[64:67]
	v_mfma_f32_16x16x32_bf16 v[60:63], v[172:175], v[204:207], v[60:63]
	v_mfma_f32_16x16x32_bf16 v[48:51], v[140:143], v[212:215], v[48:51]
	v_mfma_f32_16x16x32_bf16 v[44:47], v[172:175], v[212:215], v[44:47]
	v_mfma_f32_16x16x32_bf16 v[32:35], v[140:143], v[220:223], v[32:35]
	v_mfma_f32_16x16x32_bf16 v[28:31], v[172:175], v[220:223], v[28:31]
	v_mfma_f32_16x16x32_bf16 v[16:19], v[140:143], v[228:231], v[16:19]
	v_mfma_f32_16x16x32_bf16 v[12:15], v[172:175], v[228:231], v[12:15]
	v_mfma_f32_16x16x32_bf16 v[64:67], v[150:153], v[208:211], v[64:67]
	v_mfma_f32_16x16x32_bf16 v[60:63], v[176:179], v[208:211], v[60:63]
	v_mfma_f32_16x16x32_bf16 v[48:51], v[150:153], v[216:219], v[48:51]
	v_mfma_f32_16x16x32_bf16 v[44:47], v[176:179], v[216:219], v[44:47]
	v_mfma_f32_16x16x32_bf16 v[32:35], v[150:153], v[224:227], v[32:35]
	v_mfma_f32_16x16x32_bf16 v[28:31], v[176:179], v[224:227], v[28:31]
	v_mfma_f32_16x16x32_bf16 v[16:19], v[150:153], v[232:235], v[16:19]
	v_mfma_f32_16x16x32_bf16 v[12:15], v[176:179], v[232:235], v[12:15]
	v_mfma_f32_16x16x32_bf16 v[56:59], v[180:183], v[204:207], v[56:59]
	v_mfma_f32_16x16x32_bf16 v[52:55], v[188:191], v[204:207], v[52:55]
	v_mfma_f32_16x16x32_bf16 v[40:43], v[180:183], v[212:215], v[40:43]
	v_mfma_f32_16x16x32_bf16 v[36:39], v[188:191], v[212:215], v[36:39]
	v_mfma_f32_16x16x32_bf16 v[24:27], v[180:183], v[220:223], v[24:27]
	v_mfma_f32_16x16x32_bf16 v[20:23], v[188:191], v[220:223], v[20:23]
	v_mfma_f32_16x16x32_bf16 v[8:11], v[180:183], v[228:231], v[8:11]
	v_mfma_f32_16x16x32_bf16 v[4:7], v[188:191], v[228:231], v[4:7]
	v_mfma_f32_16x16x32_bf16 v[56:59], v[184:187], v[208:211], v[56:59]
	v_mfma_f32_16x16x32_bf16 v[52:55], v[200:203], v[208:211], v[52:55]
	v_mfma_f32_16x16x32_bf16 v[40:43], v[184:187], v[216:219], v[40:43]
	v_mfma_f32_16x16x32_bf16 v[36:39], v[200:203], v[216:219], v[36:39]
	v_mfma_f32_16x16x32_bf16 v[24:27], v[184:187], v[224:227], v[24:27]
	v_mfma_f32_16x16x32_bf16 v[20:23], v[200:203], v[224:227], v[20:23]
	v_mfma_f32_16x16x32_bf16 v[8:11], v[184:187], v[232:235], v[8:11]
	v_mfma_f32_16x16x32_bf16 v[4:7], v[200:203], v[232:235], v[4:7]
	s_setprio 0
	s_barrier
	s_add_i32 s61, s61, 2
	s_add_u32 s55, s55, 0x100
	s_addc_u32 s60, s60, 0
	s_cmp_gt_u32 s61, 41
	s_mov_b64 s[38:39], s[14:15]
	s_cbranch_scc0 .LBB0_1044
	s_and_b64 vcc, exec, s[10:11]
	s_cbranch_vccz .LBB0_1047
	s_barrier
